# GEMM steady K-loops: second k-step block's first LDS fragment reads issued under the last 2 MFMA groups of the first block (B-regrouped), on top of cross-tile pipelining
# speedup vs baseline: 1.0208x; 1.0034x over previous
; DEVI f32x4 mfma16(bf16x8 a, bf16x8 b, f32x4 c) { return __builtin_amdgcn_mfma_f32_16x16x32_bf16(a, b, c, 0, 0, 0); }
; template <int MODE, class Epi>
; DEVI void gemm256_phase(int sw, const bf16_t* __restrict__ W, int ldw, const bf16_t* __restrict__ X, int ldx, int K, int nN, char* shm, const Epi& epi) {
;     ...
;     for (int t = 0; t < ntk; ++t) {
;       const int cur = (b0 + t) & 1;
;       const bool st_own = t + 1 < ntk, st_next = !st_own && has_next;
;       if (wid < 4) {
;         if (st_own) stage(cur ^ 1, n0, m0, kt0 + t + 1);
;         else if (st_next) stage(cur ^ 1, n1, m1, kt1);
;       }
;       const char* SAp = shm + cur * STAGE_B + wr * (16 * 1024) + lds_lo;
;       const char* SBp = shm + cur * STAGE_B + TILE_B + wc * (8 * 1024) + lds_lo;
; #pragma unroll
;       for (int ks = 0; ks < 2; ++ks) {
;         const int kx = (wid >> 2) ? (1 - 2 * ks) * 1024 : 0;
;         bf16x8 At[8], Bf[4];
; #pragma unroll
;         for (int m = 0; m < 8; ++m) At[m] = *(const bf16x8*)(SAp + (2 * m + ks) * 1024 + kx);
; #pragma unroll
;         for (int n = 0; n < 4; ++n) Bf[n] = *(const bf16x8*)(SBp + (2 * n + ks) * 1024 + kx);
; #pragma unroll
;         for (int m = 0; m < 8; ++m)
; #pragma unroll
;           for (int n = 0; n < 4; ++n) acc[m][n] = mfma16(At[m], Bf[n], acc[m][n]);
;         __builtin_amdgcn_sched_barrier(0);
;         if (ks == 0 && wid >= 4) {
;           if (st_own) stage(cur ^ 1, n0, m0, kt0 + t + 1);
;           else if (st_next) stage(cur ^ 1, n1, m1, kt1);
;         }
;       }
;       asm volatile("s_waitcnt vmcnt(0)" ::: "memory");
;       __syncthreads();
;     }
.LBB0_167:
.Lmy_xs_168:
	s_waitcnt lgkmcnt(3)
	v_mfma_f32_16x16x32_bf16 v[124:127], v[220:223], v[134:137], v[124:127]
	v_mfma_f32_16x16x32_bf16 v[120:123], v[220:223], v[138:141], v[120:123]
	v_mfma_f32_16x16x32_bf16 v[116:119], v[220:223], v[142:145], v[116:119]
	v_mfma_f32_16x16x32_bf16 v[112:115], v[220:223], v[146:149], v[112:115]
	ds_read_b128 v[236:239], v150 offset:9216
	s_waitcnt lgkmcnt(3)
	v_mfma_f32_16x16x32_bf16 v[108:111], v[224:227], v[134:137], v[108:111]
	v_mfma_f32_16x16x32_bf16 v[104:107], v[224:227], v[138:141], v[104:107]
	v_mfma_f32_16x16x32_bf16 v[100:103], v[224:227], v[142:145], v[100:103]
	v_mfma_f32_16x16x32_bf16 v[96:99], v[224:227], v[146:149], v[96:99]
	ds_read_b128 v[240:243], v150 offset:11264
	s_waitcnt lgkmcnt(3)
	v_mfma_f32_16x16x32_bf16 v[92:95], v[228:231], v[134:137], v[92:95]
	v_mfma_f32_16x16x32_bf16 v[88:91], v[228:231], v[138:141], v[88:91]
	v_mfma_f32_16x16x32_bf16 v[84:87], v[228:231], v[142:145], v[84:87]
	v_mfma_f32_16x16x32_bf16 v[80:83], v[228:231], v[146:149], v[80:83]
	ds_read_b128 v[244:247], v150 offset:13312
	s_waitcnt lgkmcnt(3)
	v_mfma_f32_16x16x32_bf16 v[76:79], v[232:235], v[134:137], v[76:79]
	v_mfma_f32_16x16x32_bf16 v[72:75], v[232:235], v[138:141], v[72:75]
	v_mfma_f32_16x16x32_bf16 v[68:71], v[232:235], v[142:145], v[68:71]
	v_mfma_f32_16x16x32_bf16 v[64:67], v[232:235], v[146:149], v[64:67]
	ds_read_b128 v[248:251], v150 offset:15360
	s_waitcnt lgkmcnt(3)
	v_mfma_f32_16x16x32_bf16 v[60:63], v[236:239], v[134:137], v[60:63]
	v_mfma_f32_16x16x32_bf16 v[56:59], v[236:239], v[138:141], v[56:59]
	v_mfma_f32_16x16x32_bf16 v[52:55], v[236:239], v[142:145], v[52:55]
	v_mfma_f32_16x16x32_bf16 v[48:51], v[236:239], v[146:149], v[48:51]
	s_waitcnt lgkmcnt(2)
	v_mfma_f32_16x16x32_bf16 v[44:47], v[240:243], v[134:137], v[44:47]
	v_mfma_f32_16x16x32_bf16 v[40:43], v[240:243], v[138:141], v[40:43]
	v_mfma_f32_16x16x32_bf16 v[36:39], v[240:243], v[142:145], v[36:39]
	v_mfma_f32_16x16x32_bf16 v[32:35], v[240:243], v[146:149], v[32:35]
	s_addk_i32 s67, 0x80
	s_cmp_eq_u32 s66, s68
	s_cbranch_scc1 .Lmy_xexit_168
	s_add_i32 s0, s45, s68
	s_and_b32 s69, s0, 1
	s_add_i32 s68, s68, 1
	s_cmp_lt_i32 s68, s46
	s_cselect_b64 s[0:1], -1, 0
	s_cmp_ge_i32 s68, s46
	s_cselect_b64 s[8:9], -1, 0
	v_cndmask_b32_e64 v128, 0, 1, s[0:1]
	s_and_b64 s[8:9], s[2:3], s[8:9]
	s_andn2_b64 vcc, exec, s[36:37]
	v_cmp_ne_u32_e64 s[0:1], 1, v128
	s_lshl_b32 s10, s69, 16
	s_add_i32 s11, s10, s47
	v_add_u32_e32 v129, s11, v194
	v_add_u32_e32 v253, s53, v129
	s_or_b32 s11, s10, s52
	v_add_u32_e32 v128, s11, v194
	v_add_u32_e32 v252, s53, v128
	s_waitcnt lgkmcnt(0)
	s_waitcnt vmcnt(0)
	s_barrier
	ds_read_b128 v[220:223], v253
	v_mfma_f32_16x16x32_bf16 v[28:31], v[244:247], v[134:137], v[28:31]
	v_mfma_f32_16x16x32_bf16 v[12:15], v[248:251], v[134:137], v[12:15]
	ds_read_b128 v[134:137], v252 offset:32768
	v_mfma_f32_16x16x32_bf16 v[24:27], v[244:247], v[138:141], v[24:27]
	v_mfma_f32_16x16x32_bf16 v[8:11], v[248:251], v[138:141], v[8:11]
	ds_read_b128 v[138:141], v252 offset:34816
	v_mfma_f32_16x16x32_bf16 v[20:23], v[244:247], v[142:145], v[20:23]
	v_mfma_f32_16x16x32_bf16 v[4:7], v[248:251], v[142:145], v[4:7]
	ds_read_b128 v[142:145], v252 offset:36864
	v_mfma_f32_16x16x32_bf16 v[16:19], v[244:247], v[146:149], v[16:19]
	v_mfma_f32_16x16x32_bf16 v[0:3], v[248:251], v[146:149], v[0:3]
	ds_read_b128 v[146:149], v252 offset:38912
	ds_read_b128 v[224:227], v253 offset:2048
	ds_read_b128 v[228:231], v253 offset:4096
	ds_read_b128 v[232:235], v253 offset:6144
	v_mov_b32_e32 v150, v253
	s_branch .Lmy_xf_168

; DEVI f32x4 mfma16(bf16x8 a, bf16x8 b, f32x4 c) { return __builtin_amdgcn_mfma_f32_16x16x32_bf16(a, b, c, 0, 0, 0); }
; template <int MODE, class Epi>
; DEVI void gemm256_phase(int sw, const bf16_t* __restrict__ W, int ldw, const bf16_t* __restrict__ X, int ldx, int K, int nN, char* shm, const Epi& epi) {
;     ...
;   auto stage = [&](int buf, int n0, int m0, int kt) {
;     const char* wk = (const char*)(W + (size_t)n0 * ldw) + kt * 128;
;     const char* xk = (const char*)(X + (size_t)m0 * ldx) + kt * 128;
; #pragma unroll
;     for (int i = 0; i < 4; ++i) {
;       unsigned ow = offW[i], ox = offX[i];
;       asm volatile("" : "+v"(ow), "+v"(ox));
;       __builtin_amdgcn_global_load_lds((const unsigned*)(wk + ow), (unsigned*)(shm + buf * STAGE_B + wid * 1024 + i * 8192), 16, 0, 0);
;       __builtin_amdgcn_global_load_lds((const unsigned*)(xk + ox), (unsigned*)(shm + buf * STAGE_B + TILE_B + wid * 1024 + i * 8192), 16, 0, 0);
;     }
;     ...
;       for (int ks = 0; ks < 2; ++ks) {
;         const int kx = (wid >> 2) ? (1 - 2 * ks) * 1024 : 0;
;         bf16x8 At[8], Bf[4];
; #pragma unroll
;         for (int m = 0; m < 8; ++m) At[m] = *(const bf16x8*)(SAp + (2 * m + ks) * 1024 + kx);
; #pragma unroll
;         for (int n = 0; n < 4; ++n) Bf[n] = *(const bf16x8*)(SBp + (2 * n + ks) * 1024 + kx);
; #pragma unroll
;         for (int m = 0; m < 8; ++m)
; #pragma unroll
;           for (int n = 0; n < 4; ++n) acc[m][n] = mfma16(At[m], Bf[n], acc[m][n]);
;         __builtin_amdgcn_sched_barrier(0);
;         if (ks == 0 && wid >= 4) {
;           if (st_own) stage(cur ^ 1, n0, m0, kt0 + t + 1);
;           else if (st_next) stage(cur ^ 1, n1, m1, kt1);
;         }
.Lmy_xf_168:
	s_add_u32 s98, s62, s67
	s_addc_u32 s99, s63, 0
	s_add_u32 s98, s98, 0x80
	s_addc_u32 s99, s99, 0
	s_add_u32 s100, s64, s67
	s_addc_u32 s101, s65, 0
	s_add_u32 s100, s100, 0x80
	s_addc_u32 s101, s101, 0
	s_xor_b32 m0, s10, 0x10000
	s_add_i32 m0, m0, s44
	s_waitcnt lgkmcnt(3)
	v_mfma_f32_16x16x32_bf16 v[124:127], v[220:223], v[134:137], v[124:127]
	v_mfma_f32_16x16x32_bf16 v[120:123], v[220:223], v[138:141], v[120:123]
	v_mfma_f32_16x16x32_bf16 v[116:119], v[220:223], v[142:145], v[116:119]
	v_mfma_f32_16x16x32_bf16 v[112:115], v[220:223], v[146:149], v[112:115]
	global_load_lds_dwordx4 v190, s[98:99]
	ds_read_b128 v[236:239], v150 offset:8192
	s_add_i32 m0, m0, 0x8000
	s_waitcnt lgkmcnt(3)
	v_mfma_f32_16x16x32_bf16 v[108:111], v[224:227], v[134:137], v[108:111]
	v_mfma_f32_16x16x32_bf16 v[104:107], v[224:227], v[138:141], v[104:107]
	v_mfma_f32_16x16x32_bf16 v[100:103], v[224:227], v[142:145], v[100:103]
	v_mfma_f32_16x16x32_bf16 v[96:99], v[224:227], v[146:149], v[96:99]
	global_load_lds_dwordx4 v190, s[100:101]
	ds_read_b128 v[240:243], v150 offset:10240
	s_add_i32 m0, m0, 0xffffa000
	s_waitcnt lgkmcnt(3)
	v_mfma_f32_16x16x32_bf16 v[92:95], v[228:231], v[134:137], v[92:95]
	v_mfma_f32_16x16x32_bf16 v[88:91], v[228:231], v[138:141], v[88:91]
	v_mfma_f32_16x16x32_bf16 v[84:87], v[228:231], v[142:145], v[84:87]
	v_mfma_f32_16x16x32_bf16 v[80:83], v[228:231], v[146:149], v[80:83]
	global_load_lds_dwordx4 v191, s[98:99]
	ds_read_b128 v[244:247], v150 offset:12288
	s_add_i32 m0, m0, 0x8000
	s_waitcnt lgkmcnt(3)
	v_mfma_f32_16x16x32_bf16 v[76:79], v[232:235], v[134:137], v[76:79]
	v_mfma_f32_16x16x32_bf16 v[72:75], v[232:235], v[138:141], v[72:75]
	v_mfma_f32_16x16x32_bf16 v[68:71], v[232:235], v[142:145], v[68:71]
	v_mfma_f32_16x16x32_bf16 v[64:67], v[232:235], v[146:149], v[64:67]
	global_load_lds_dwordx4 v191, s[100:101]
	ds_read_b128 v[248:251], v150 offset:14336
	s_add_i32 m0, m0, 0xffffa000
	s_waitcnt lgkmcnt(3)
	v_mfma_f32_16x16x32_bf16 v[60:63], v[236:239], v[134:137], v[60:63]
	v_mfma_f32_16x16x32_bf16 v[56:59], v[236:239], v[138:141], v[56:59]
	v_mfma_f32_16x16x32_bf16 v[52:55], v[236:239], v[142:145], v[52:55]
	v_mfma_f32_16x16x32_bf16 v[48:51], v[236:239], v[146:149], v[48:51]
	global_load_lds_dwordx4 v192, s[98:99]
	s_add_i32 m0, m0, 0x8000
	s_waitcnt lgkmcnt(2)
	v_mfma_f32_16x16x32_bf16 v[44:47], v[240:243], v[134:137], v[44:47]
	v_mfma_f32_16x16x32_bf16 v[40:43], v[240:243], v[138:141], v[40:43]
	v_mfma_f32_16x16x32_bf16 v[36:39], v[240:243], v[142:145], v[36:39]
	v_mfma_f32_16x16x32_bf16 v[32:35], v[240:243], v[146:149], v[32:35]
	global_load_lds_dwordx4 v192, s[100:101]
	s_add_i32 m0, m0, 0xffffa000
	s_waitcnt lgkmcnt(0)
	v_add_u32_e32 v150, s54, v129
	v_add_u32_e32 v128, s54, v128
	ds_read_b128 v[220:223], v150 offset:1024
	v_mfma_f32_16x16x32_bf16 v[28:31], v[244:247], v[134:137], v[28:31]
	v_mfma_f32_16x16x32_bf16 v[12:15], v[248:251], v[134:137], v[12:15]
	ds_read_b128 v[134:137], v128 offset:33792
	v_mfma_f32_16x16x32_bf16 v[24:27], v[244:247], v[138:141], v[24:27]
	v_mfma_f32_16x16x32_bf16 v[8:11], v[248:251], v[138:141], v[8:11]
	ds_read_b128 v[138:141], v128 offset:35840
	global_load_lds_dwordx4 v193, s[98:99]
	s_add_i32 m0, m0, 0x8000
	v_mfma_f32_16x16x32_bf16 v[20:23], v[244:247], v[142:145], v[20:23]
	v_mfma_f32_16x16x32_bf16 v[4:7], v[248:251], v[142:145], v[4:7]
	ds_read_b128 v[142:145], v128 offset:37888
	v_mfma_f32_16x16x32_bf16 v[16:19], v[244:247], v[146:149], v[16:19]
	v_mfma_f32_16x16x32_bf16 v[0:3], v[248:251], v[146:149], v[0:3]
	ds_read_b128 v[146:149], v128 offset:39936
	global_load_lds_dwordx4 v193, s[100:101]
	ds_read_b128 v[224:227], v150 offset:3072
	ds_read_b128 v[228:231], v150 offset:5120
	ds_read_b128 v[232:235], v150 offset:7168
	s_andn2_b64 vcc, exec, s[30:31]
	s_branch .Lmy_xs_168
	s_and_b64 vcc, exec, s[0:1]
	s_xor_b32 s42, s10, 0x10000
	s_cbranch_vccnz .LBB0_180
	s_ashr_i32 s10, s67, 31
	s_add_u32 s12, s62, s67
	s_addc_u32 s13, s63, s10
	s_add_u32 s0, s12, 0x80
	s_addc_u32 s1, s13, 0
	s_add_u32 s14, s64, s67
	s_addc_u32 s15, s65, s10
	s_add_u32 s10, s14, 0x80
	v_mov_b32_e32 v130, v190
	v_mov_b32_e32 v188, v190
	s_addc_u32 s11, s15, 0
	s_add_i32 s43, s44, s42
	v_lshl_add_u64 v[132:133], s[12:13], 0, v[188:189]
	v_mov_b32_e32 v131, v189
	v_lshl_add_u64 v[132:133], v[132:133], 0, s[38:39]
	s_mov_b32 m0, s43
	v_lshl_add_u64 v[130:131], s[14:15], 0, v[130:131]
	global_load_lds_dwordx4 v[132:133], off
	v_lshl_add_u64 v[130:131], v[130:131], 0, s[38:39]
	s_add_i32 m0, s43, 0x8000
	v_mov_b32_e32 v188, v191
	global_load_lds_dwordx4 v[130:131], off
	v_mov_b32_e32 v130, v191
	v_mov_b32_e32 v131, v189
	v_lshl_add_u64 v[132:133], s[12:13], 0, v[188:189]
	v_lshl_add_u64 v[132:133], v[132:133], 0, s[38:39]
	s_add_i32 m0, s43, 0x2000
	v_lshl_add_u64 v[130:131], s[14:15], 0, v[130:131]
	global_load_lds_dwordx4 v[132:133], off
	v_lshl_add_u64 v[130:131], v[130:131], 0, s[38:39]
	s_add_i32 m0, s43, 0xa000
	v_mov_b32_e32 v188, v192
	global_load_lds_dwordx4 v[130:131], off
	v_mov_b32_e32 v130, v192
	v_mov_b32_e32 v131, v189
	v_lshl_add_u64 v[132:133], s[12:13], 0, v[188:189]
	v_lshl_add_u64 v[132:133], v[132:133], 0, s[38:39]
	s_add_i32 m0, s43, 0x4000
	v_lshl_add_u64 v[130:131], s[14:15], 0, v[130:131]
	global_load_lds_dwordx4 v[132:133], off
	v_lshl_add_u64 v[130:131], v[130:131], 0, s[38:39]
	s_add_i32 m0, s43, 0xc000
	s_nop 0
	global_load_lds_dwordx4 v[130:131], off
	v_mov_b32_e32 v130, v193
	v_mov_b32_e32 v131, v193
	s_mov_b64 s[12:13], -1
	s_cbranch_execz .LBB0_181
	s_branch .LBB0_184

; DEVI f32x4 mfma16(bf16x8 a, bf16x8 b, f32x4 c) { return __builtin_amdgcn_mfma_f32_16x16x32_bf16(a, b, c, 0, 0, 0); }
; template <int MODE, class Epi>
; DEVI void gemm256_phase(int sw, const bf16_t* __restrict__ W, int ldw, const bf16_t* __restrict__ X, int ldx, int K, int nN, char* shm, const Epi& epi) {
;     ...
;     for (int t = 0; t < ntk; ++t) {
;       const int cur = (b0 + t) & 1;
;       const bool st_own = t + 1 < ntk, st_next = !st_own && has_next;
;       if (wid < 4) {
;         if (st_own) stage(cur ^ 1, n0, m0, kt0 + t + 1);
;         else if (st_next) stage(cur ^ 1, n1, m1, kt1);
;       }
;       const char* SAp = shm + cur * STAGE_B + wr * (16 * 1024) + lds_lo;
;       const char* SBp = shm + cur * STAGE_B + TILE_B + wc * (8 * 1024) + lds_lo;
; #pragma unroll
;       for (int ks = 0; ks < 2; ++ks) {
;         const int kx = (wid >> 2) ? (1 - 2 * ks) * 1024 : 0;
;         bf16x8 At[8], Bf[4];
; #pragma unroll
;         for (int m = 0; m < 8; ++m) At[m] = *(const bf16x8*)(SAp + (2 * m + ks) * 1024 + kx);
; #pragma unroll
;         for (int n = 0; n < 4; ++n) Bf[n] = *(const bf16x8*)(SBp + (2 * n + ks) * 1024 + kx);
; #pragma unroll
;         for (int m = 0; m < 8; ++m)
; #pragma unroll
;           for (int n = 0; n < 4; ++n) acc[m][n] = mfma16(At[m], Bf[n], acc[m][n]);
;         __builtin_amdgcn_sched_barrier(0);
;         if (ks == 0 && wid >= 4) {
;           if (st_own) stage(cur ^ 1, n0, m0, kt0 + t + 1);
;           else if (st_next) stage(cur ^ 1, n1, m1, kt1);
;         }
;       }
;       asm volatile("s_waitcnt vmcnt(0)" ::: "memory");
;       __syncthreads();
;     }
.LBB0_703:
.Lmy_xs_704:
	s_waitcnt lgkmcnt(2)
	v_mfma_f32_16x16x32_bf16 v[124:127], v[220:223], v[134:137], v[124:127]
	v_mfma_f32_16x16x32_bf16 v[120:123], v[220:223], v[142:145], v[120:123]
	v_mfma_f32_16x16x32_bf16 v[116:119], v[220:223], v[146:149], v[116:119]
	v_mfma_f32_16x16x32_bf16 v[112:115], v[220:223], v[150:153], v[112:115]
	ds_read_b128 v[236:239], v154 offset:9216
	s_waitcnt lgkmcnt(3)
	v_mfma_f32_16x16x32_bf16 v[108:111], v[224:227], v[134:137], v[108:111]
	v_mfma_f32_16x16x32_bf16 v[104:107], v[224:227], v[142:145], v[104:107]
	v_mfma_f32_16x16x32_bf16 v[100:103], v[224:227], v[146:149], v[100:103]
	v_mfma_f32_16x16x32_bf16 v[96:99], v[224:227], v[150:153], v[96:99]
	ds_read_b128 v[240:243], v154 offset:11264
	s_waitcnt lgkmcnt(3)
	v_mfma_f32_16x16x32_bf16 v[92:95], v[228:231], v[134:137], v[92:95]
	v_mfma_f32_16x16x32_bf16 v[88:91], v[228:231], v[142:145], v[88:91]
	v_mfma_f32_16x16x32_bf16 v[84:87], v[228:231], v[146:149], v[84:87]
	v_mfma_f32_16x16x32_bf16 v[80:83], v[228:231], v[150:153], v[80:83]
	ds_read_b128 v[244:247], v154 offset:13312
	s_waitcnt lgkmcnt(3)
	v_mfma_f32_16x16x32_bf16 v[76:79], v[232:235], v[134:137], v[76:79]
	v_mfma_f32_16x16x32_bf16 v[72:75], v[232:235], v[142:145], v[72:75]
	v_mfma_f32_16x16x32_bf16 v[68:71], v[232:235], v[146:149], v[68:71]
	v_mfma_f32_16x16x32_bf16 v[64:67], v[232:235], v[150:153], v[64:67]
	ds_read_b128 v[248:251], v154 offset:15360
	s_waitcnt lgkmcnt(3)
	v_mfma_f32_16x16x32_bf16 v[60:63], v[236:239], v[134:137], v[60:63]
	v_mfma_f32_16x16x32_bf16 v[56:59], v[236:239], v[142:145], v[56:59]
	v_mfma_f32_16x16x32_bf16 v[52:55], v[236:239], v[146:149], v[52:55]
	v_mfma_f32_16x16x32_bf16 v[48:51], v[236:239], v[150:153], v[48:51]
	s_waitcnt lgkmcnt(2)
	v_mfma_f32_16x16x32_bf16 v[44:47], v[240:243], v[134:137], v[44:47]
	v_mfma_f32_16x16x32_bf16 v[40:43], v[240:243], v[142:145], v[40:43]
	v_mfma_f32_16x16x32_bf16 v[36:39], v[240:243], v[146:149], v[36:39]
	v_mfma_f32_16x16x32_bf16 v[32:35], v[240:243], v[150:153], v[32:35]
	s_addk_i32 s81, 0x80
	s_cmp_eq_u32 s80, s82
	s_cbranch_scc1 .Lmy_xexit_704
	s_add_i32 s0, s61, s82
	s_and_b32 s83, s0, 1
	s_add_i32 s82, s82, 1
	s_cmp_lt_i32 s82, s54
	s_cselect_b64 s[0:1], -1, 0
	s_cmp_ge_i32 s82, s54
	s_cselect_b64 s[40:41], -1, 0
	v_cmp_ne_u32_e32 vcc, 1, v197
	v_cndmask_b32_e64 v128, 0, 1, s[0:1]
	s_and_b64 s[40:41], s[38:39], s[40:41]
	v_cmp_ne_u32_e64 s[0:1], 1, v128
	s_lshl_b32 s42, s83, 16
	s_add_i32 s43, s42, s58
	v_add_u32_e32 v129, s43, v194
	v_add_u32_e32 v253, s62, v129
	s_or_b32 s43, s42, s59
	v_add_u32_e32 v128, s43, v194
	v_add_u32_e32 v252, s62, v128
	s_waitcnt lgkmcnt(0)
	s_waitcnt vmcnt(0)
	s_barrier
	ds_read_b128 v[220:223], v253
	ds_read_b128 v[138:141], v252 offset:34816
	v_mfma_f32_16x16x32_bf16 v[28:31], v[244:247], v[134:137], v[28:31]
	v_mfma_f32_16x16x32_bf16 v[12:15], v[248:251], v[134:137], v[12:15]
	ds_read_b128 v[134:137], v252 offset:32768
	v_mfma_f32_16x16x32_bf16 v[24:27], v[244:247], v[142:145], v[24:27]
	v_mfma_f32_16x16x32_bf16 v[8:11], v[248:251], v[142:145], v[8:11]
	ds_read_b128 v[142:145], v252 offset:36864
	v_mfma_f32_16x16x32_bf16 v[20:23], v[244:247], v[146:149], v[20:23]
	v_mfma_f32_16x16x32_bf16 v[4:7], v[248:251], v[146:149], v[4:7]
	ds_read_b128 v[146:149], v252 offset:38912
	v_mfma_f32_16x16x32_bf16 v[16:19], v[244:247], v[150:153], v[16:19]
	v_mfma_f32_16x16x32_bf16 v[0:3], v[248:251], v[150:153], v[0:3]
	ds_read_b128 v[224:227], v253 offset:2048
	ds_read_b128 v[228:231], v253 offset:4096
	ds_read_b128 v[232:235], v253 offset:6144
	v_mov_b32_e32 v150, v253
	s_branch .Lmy_xf_704

; DEVI f32x4 mfma16(bf16x8 a, bf16x8 b, f32x4 c) { return __builtin_amdgcn_mfma_f32_16x16x32_bf16(a, b, c, 0, 0, 0); }
; template <int MODE, class Epi>
; DEVI void gemm256_phase(int sw, const bf16_t* __restrict__ W, int ldw, const bf16_t* __restrict__ X, int ldx, int K, int nN, char* shm, const Epi& epi) {
;     ...
;   auto stage = [&](int buf, int n0, int m0, int kt) {
;     const char* wk = (const char*)(W + (size_t)n0 * ldw) + kt * 128;
;     const char* xk = (const char*)(X + (size_t)m0 * ldx) + kt * 128;
; #pragma unroll
;     for (int i = 0; i < 4; ++i) {
;       unsigned ow = offW[i], ox = offX[i];
;       asm volatile("" : "+v"(ow), "+v"(ox));
;       __builtin_amdgcn_global_load_lds((const unsigned*)(wk + ow), (unsigned*)(shm + buf * STAGE_B + wid * 1024 + i * 8192), 16, 0, 0);
;       __builtin_amdgcn_global_load_lds((const unsigned*)(xk + ox), (unsigned*)(shm + buf * STAGE_B + TILE_B + wid * 1024 + i * 8192), 16, 0, 0);
;     }
;     ...
;       for (int ks = 0; ks < 2; ++ks) {
;         const int kx = (wid >> 2) ? (1 - 2 * ks) * 1024 : 0;
;         bf16x8 At[8], Bf[4];
; #pragma unroll
;         for (int m = 0; m < 8; ++m) At[m] = *(const bf16x8*)(SAp + (2 * m + ks) * 1024 + kx);
; #pragma unroll
;         for (int n = 0; n < 4; ++n) Bf[n] = *(const bf16x8*)(SBp + (2 * n + ks) * 1024 + kx);
; #pragma unroll
;         for (int m = 0; m < 8; ++m)
; #pragma unroll
;           for (int n = 0; n < 4; ++n) acc[m][n] = mfma16(At[m], Bf[n], acc[m][n]);
;         __builtin_amdgcn_sched_barrier(0);
;         if (ks == 0 && wid >= 4) {
;           if (st_own) stage(cur ^ 1, n0, m0, kt0 + t + 1);
;           else if (st_next) stage(cur ^ 1, n1, m1, kt1);
;         }
.Lmy_xf_704:
	s_add_u32 s98, s78, s81
	s_addc_u32 s99, s79, 0
	s_add_u32 s98, s98, 0x80
	s_addc_u32 s99, s99, 0
	s_add_u32 s100, s76, s81
	s_addc_u32 s101, s77, 0
	s_add_u32 s100, s100, 0x80
	s_addc_u32 s101, s101, 0
	s_xor_b32 m0, s42, 0x10000
	s_add_i32 m0, m0, s57
	s_waitcnt lgkmcnt(3)
	v_mfma_f32_16x16x32_bf16 v[124:127], v[220:223], v[134:137], v[124:127]
	v_mfma_f32_16x16x32_bf16 v[120:123], v[220:223], v[138:141], v[120:123]
	v_mfma_f32_16x16x32_bf16 v[116:119], v[220:223], v[142:145], v[116:119]
	v_mfma_f32_16x16x32_bf16 v[112:115], v[220:223], v[146:149], v[112:115]
	global_load_lds_dwordx4 v190, s[98:99]
	ds_read_b128 v[236:239], v150 offset:8192
	s_add_i32 m0, m0, 0x8000
	s_waitcnt lgkmcnt(3)
	v_mfma_f32_16x16x32_bf16 v[108:111], v[224:227], v[134:137], v[108:111]
	v_mfma_f32_16x16x32_bf16 v[104:107], v[224:227], v[138:141], v[104:107]
	v_mfma_f32_16x16x32_bf16 v[100:103], v[224:227], v[142:145], v[100:103]
	v_mfma_f32_16x16x32_bf16 v[96:99], v[224:227], v[146:149], v[96:99]
	global_load_lds_dwordx4 v190, s[100:101]
	ds_read_b128 v[240:243], v150 offset:10240
	s_add_i32 m0, m0, 0xffffa000
	s_waitcnt lgkmcnt(3)
	v_mfma_f32_16x16x32_bf16 v[92:95], v[228:231], v[134:137], v[92:95]
	v_mfma_f32_16x16x32_bf16 v[88:91], v[228:231], v[138:141], v[88:91]
	v_mfma_f32_16x16x32_bf16 v[84:87], v[228:231], v[142:145], v[84:87]
	v_mfma_f32_16x16x32_bf16 v[80:83], v[228:231], v[146:149], v[80:83]
	global_load_lds_dwordx4 v191, s[98:99]
	ds_read_b128 v[244:247], v150 offset:12288
	s_add_i32 m0, m0, 0x8000
	s_waitcnt lgkmcnt(3)
	v_mfma_f32_16x16x32_bf16 v[76:79], v[232:235], v[134:137], v[76:79]
	v_mfma_f32_16x16x32_bf16 v[72:75], v[232:235], v[138:141], v[72:75]
	v_mfma_f32_16x16x32_bf16 v[68:71], v[232:235], v[142:145], v[68:71]
	v_mfma_f32_16x16x32_bf16 v[64:67], v[232:235], v[146:149], v[64:67]
	global_load_lds_dwordx4 v191, s[100:101]
	ds_read_b128 v[248:251], v150 offset:14336
	s_add_i32 m0, m0, 0xffffa000
	s_waitcnt lgkmcnt(3)
	v_mfma_f32_16x16x32_bf16 v[60:63], v[236:239], v[134:137], v[60:63]
	v_mfma_f32_16x16x32_bf16 v[56:59], v[236:239], v[138:141], v[56:59]
	v_mfma_f32_16x16x32_bf16 v[52:55], v[236:239], v[142:145], v[52:55]
	v_mfma_f32_16x16x32_bf16 v[48:51], v[236:239], v[146:149], v[48:51]
	global_load_lds_dwordx4 v192, s[98:99]
	s_add_i32 m0, m0, 0x8000
	s_waitcnt lgkmcnt(2)
	v_mfma_f32_16x16x32_bf16 v[44:47], v[240:243], v[134:137], v[44:47]
	v_mfma_f32_16x16x32_bf16 v[40:43], v[240:243], v[138:141], v[40:43]
	v_mfma_f32_16x16x32_bf16 v[36:39], v[240:243], v[142:145], v[36:39]
	v_mfma_f32_16x16x32_bf16 v[32:35], v[240:243], v[146:149], v[32:35]
	global_load_lds_dwordx4 v192, s[100:101]
	s_add_i32 m0, m0, 0xffffa000
	s_waitcnt lgkmcnt(0)
	v_add_u32_e32 v154, s63, v129
	v_add_u32_e32 v128, s63, v128
	ds_read_b128 v[220:223], v154 offset:1024
	ds_read_b128 v[224:227], v154 offset:3072
	ds_read_b128 v[150:153], v128 offset:39936
	v_mfma_f32_16x16x32_bf16 v[28:31], v[244:247], v[134:137], v[28:31]
	v_mfma_f32_16x16x32_bf16 v[12:15], v[248:251], v[134:137], v[12:15]
	ds_read_b128 v[134:137], v128 offset:33792
	v_mfma_f32_16x16x32_bf16 v[24:27], v[244:247], v[138:141], v[24:27]
	v_mfma_f32_16x16x32_bf16 v[8:11], v[248:251], v[138:141], v[8:11]
	global_load_lds_dwordx4 v193, s[98:99]
	s_add_i32 m0, m0, 0x8000
	v_mfma_f32_16x16x32_bf16 v[20:23], v[244:247], v[142:145], v[20:23]
	v_mfma_f32_16x16x32_bf16 v[4:7], v[248:251], v[142:145], v[4:7]
	ds_read_b128 v[142:145], v128 offset:35840
	v_mfma_f32_16x16x32_bf16 v[16:19], v[244:247], v[146:149], v[16:19]
	v_mfma_f32_16x16x32_bf16 v[0:3], v[248:251], v[146:149], v[0:3]
	ds_read_b128 v[146:149], v128 offset:37888
	global_load_lds_dwordx4 v193, s[100:101]
	ds_read_b128 v[228:231], v154 offset:5120
	ds_read_b128 v[232:235], v154 offset:7168
	s_andn2_b64 vcc, exec, s[8:9]
	s_branch .Lmy_xs_704
	s_and_b64 vcc, exec, s[0:1]
	s_xor_b32 s52, s42, 0x10000
	s_cbranch_vccnz .LBB0_716
	s_ashr_i32 s42, s81, 31
	s_add_u32 s44, s78, s81
	s_addc_u32 s45, s79, s42
	s_add_u32 s0, s44, 0x80
	s_addc_u32 s1, s45, 0
	s_add_u32 s46, s76, s81
	s_addc_u32 s47, s77, s42
	s_add_u32 s42, s46, 0x80
	v_mov_b32_e32 v188, v190
	v_mov_b32_e32 v130, v190
	s_addc_u32 s43, s47, 0
	s_add_i32 s53, s57, s52
	v_lshl_add_u64 v[132:133], s[44:45], 0, v[188:189]
	v_mov_b32_e32 v131, v189
	v_lshl_add_u64 v[132:133], v[132:133], 0, s[10:11]
	s_mov_b32 m0, s53
	v_lshl_add_u64 v[130:131], s[46:47], 0, v[130:131]
	global_load_lds_dwordx4 v[132:133], off
	v_lshl_add_u64 v[130:131], v[130:131], 0, s[10:11]
	s_add_i32 m0, s53, 0x8000
	v_mov_b32_e32 v188, v191
	global_load_lds_dwordx4 v[130:131], off
	v_mov_b32_e32 v130, v191
	v_mov_b32_e32 v131, v189
	v_lshl_add_u64 v[132:133], s[44:45], 0, v[188:189]
	v_lshl_add_u64 v[132:133], v[132:133], 0, s[10:11]
	s_add_i32 m0, s53, 0x2000
	v_lshl_add_u64 v[130:131], s[46:47], 0, v[130:131]
	global_load_lds_dwordx4 v[132:133], off
	v_lshl_add_u64 v[130:131], v[130:131], 0, s[10:11]
	s_add_i32 m0, s53, 0xa000
	v_mov_b32_e32 v188, v192
	global_load_lds_dwordx4 v[130:131], off
	v_mov_b32_e32 v130, v192
	v_mov_b32_e32 v131, v189
	v_lshl_add_u64 v[132:133], s[44:45], 0, v[188:189]
	v_lshl_add_u64 v[132:133], v[132:133], 0, s[10:11]
	s_add_i32 m0, s53, 0x4000
	v_lshl_add_u64 v[130:131], s[46:47], 0, v[130:131]
	global_load_lds_dwordx4 v[132:133], off
	v_lshl_add_u64 v[130:131], v[130:131], 0, s[10:11]
	s_add_i32 m0, s53, 0xc000
	s_nop 0
	global_load_lds_dwordx4 v[130:131], off
	v_mov_b32_e32 v130, v193
	v_mov_b32_e32 v131, v193
	s_mov_b64 s[44:45], -1
	s_cbranch_execz .LBB0_717
	s_branch .LBB0_720

; DEVI f32x4 mfma16(bf16x8 a, bf16x8 b, f32x4 c) { return __builtin_amdgcn_mfma_f32_16x16x32_bf16(a, b, c, 0, 0, 0); }
; template <int MODE, class Epi>
; DEVI void gemm256_phase(int sw, const bf16_t* __restrict__ W, int ldw, const bf16_t* __restrict__ X, int ldx, int K, int nN, char* shm, const Epi& epi) {
;     ...
;     for (int t = 0; t < ntk; ++t) {
;       const int cur = (b0 + t) & 1;
;       const bool st_own = t + 1 < ntk, st_next = !st_own && has_next;
;       if (wid < 4) {
;         if (st_own) stage(cur ^ 1, n0, m0, kt0 + t + 1);
;         else if (st_next) stage(cur ^ 1, n1, m1, kt1);
;       }
;       const char* SAp = shm + cur * STAGE_B + wr * (16 * 1024) + lds_lo;
;       const char* SBp = shm + cur * STAGE_B + TILE_B + wc * (8 * 1024) + lds_lo;
; #pragma unroll
;       for (int ks = 0; ks < 2; ++ks) {
;         const int kx = (wid >> 2) ? (1 - 2 * ks) * 1024 : 0;
;         bf16x8 At[8], Bf[4];
; #pragma unroll
;         for (int m = 0; m < 8; ++m) At[m] = *(const bf16x8*)(SAp + (2 * m + ks) * 1024 + kx);
; #pragma unroll
;         for (int n = 0; n < 4; ++n) Bf[n] = *(const bf16x8*)(SBp + (2 * n + ks) * 1024 + kx);
; #pragma unroll
;         for (int m = 0; m < 8; ++m)
; #pragma unroll
;           for (int n = 0; n < 4; ++n) acc[m][n] = mfma16(At[m], Bf[n], acc[m][n]);
;         __builtin_amdgcn_sched_barrier(0);
;         if (ks == 0 && wid >= 4) {
;           if (st_own) stage(cur ^ 1, n0, m0, kt0 + t + 1);
;           else if (st_next) stage(cur ^ 1, n1, m1, kt1);
;         }
;       }
;       asm volatile("s_waitcnt vmcnt(0)" ::: "memory");
;       __syncthreads();
;     }
.LBB0_984:
.Lmy_xs_985:
	s_waitcnt lgkmcnt(2)
	v_mfma_f32_16x16x32_bf16 v[124:127], v[220:223], v[134:137], v[124:127]
	v_mfma_f32_16x16x32_bf16 v[120:123], v[220:223], v[142:145], v[120:123]
	v_mfma_f32_16x16x32_bf16 v[116:119], v[220:223], v[146:149], v[116:119]
	v_mfma_f32_16x16x32_bf16 v[112:115], v[220:223], v[150:153], v[112:115]
	ds_read_b128 v[236:239], v154 offset:9216
	s_waitcnt lgkmcnt(3)
	v_mfma_f32_16x16x32_bf16 v[108:111], v[224:227], v[134:137], v[108:111]
	v_mfma_f32_16x16x32_bf16 v[104:107], v[224:227], v[142:145], v[104:107]
	v_mfma_f32_16x16x32_bf16 v[100:103], v[224:227], v[146:149], v[100:103]
	v_mfma_f32_16x16x32_bf16 v[96:99], v[224:227], v[150:153], v[96:99]
	ds_read_b128 v[240:243], v154 offset:11264
	s_waitcnt lgkmcnt(3)
	v_mfma_f32_16x16x32_bf16 v[92:95], v[228:231], v[134:137], v[92:95]
	v_mfma_f32_16x16x32_bf16 v[88:91], v[228:231], v[142:145], v[88:91]
	v_mfma_f32_16x16x32_bf16 v[84:87], v[228:231], v[146:149], v[84:87]
	v_mfma_f32_16x16x32_bf16 v[80:83], v[228:231], v[150:153], v[80:83]
	ds_read_b128 v[244:247], v154 offset:13312
	s_waitcnt lgkmcnt(3)
	v_mfma_f32_16x16x32_bf16 v[76:79], v[232:235], v[134:137], v[76:79]
	v_mfma_f32_16x16x32_bf16 v[72:75], v[232:235], v[142:145], v[72:75]
	v_mfma_f32_16x16x32_bf16 v[68:71], v[232:235], v[146:149], v[68:71]
	v_mfma_f32_16x16x32_bf16 v[64:67], v[232:235], v[150:153], v[64:67]
	ds_read_b128 v[248:251], v154 offset:15360
	s_waitcnt lgkmcnt(3)
	v_mfma_f32_16x16x32_bf16 v[60:63], v[236:239], v[134:137], v[60:63]
	v_mfma_f32_16x16x32_bf16 v[56:59], v[236:239], v[142:145], v[56:59]
	v_mfma_f32_16x16x32_bf16 v[52:55], v[236:239], v[146:149], v[52:55]
	v_mfma_f32_16x16x32_bf16 v[48:51], v[236:239], v[150:153], v[48:51]
	s_waitcnt lgkmcnt(2)
	v_mfma_f32_16x16x32_bf16 v[44:47], v[240:243], v[134:137], v[44:47]
	v_mfma_f32_16x16x32_bf16 v[40:43], v[240:243], v[142:145], v[40:43]
	v_mfma_f32_16x16x32_bf16 v[36:39], v[240:243], v[146:149], v[36:39]
	v_mfma_f32_16x16x32_bf16 v[32:35], v[240:243], v[150:153], v[32:35]
	s_addk_i32 s57, 0x80
	s_cmp_eq_u32 s54, s58
	s_cbranch_scc1 .Lmy_xexit_985
	s_add_i32 s10, s37, s58
	s_and_b32 s60, s10, 1
	s_mov_b64 s[10:11], -1
	s_and_b64 vcc, exec, s[4:5]
	s_lshl_b32 s59, s60, 16
	s_add_i32 s10, s59, s38
	v_add_u32_e32 v129, s10, v198
	v_add_u32_e32 v253, s41, v129
	s_add_i32 s10, s59, s39
	v_add_u32_e32 v128, s10, v198
	v_add_u32_e32 v252, s41, v128
	s_waitcnt lgkmcnt(0)
	s_waitcnt vmcnt(0)
	s_barrier
	ds_read_b128 v[220:223], v253
	ds_read_b128 v[224:227], v253 offset:2048
	v_mfma_f32_16x16x32_bf16 v[28:31], v[244:247], v[134:137], v[28:31]
	v_mfma_f32_16x16x32_bf16 v[12:15], v[248:251], v[134:137], v[12:15]
	ds_read_b128 v[134:137], v252 offset:32768
	v_mfma_f32_16x16x32_bf16 v[24:27], v[244:247], v[142:145], v[24:27]
	v_mfma_f32_16x16x32_bf16 v[8:11], v[248:251], v[142:145], v[8:11]
	ds_read_b128 v[142:145], v252 offset:34816
	v_mfma_f32_16x16x32_bf16 v[20:23], v[244:247], v[146:149], v[20:23]
	v_mfma_f32_16x16x32_bf16 v[4:7], v[248:251], v[146:149], v[4:7]
	ds_read_b128 v[146:149], v252 offset:36864
	v_mfma_f32_16x16x32_bf16 v[16:19], v[244:247], v[150:153], v[16:19]
	v_mfma_f32_16x16x32_bf16 v[0:3], v[248:251], v[150:153], v[0:3]
	ds_read_b128 v[150:153], v252 offset:38912
	ds_read_b128 v[228:231], v253 offset:4096
	ds_read_b128 v[232:235], v253 offset:6144
	v_mov_b32_e32 v154, v253
	s_branch .Lmy_xf_985

; DEVI f32x4 mfma16(bf16x8 a, bf16x8 b, f32x4 c) { return __builtin_amdgcn_mfma_f32_16x16x32_bf16(a, b, c, 0, 0, 0); }
; template <int MODE, class Epi>
; DEVI void gemm256_phase(int sw, const bf16_t* __restrict__ W, int ldw, const bf16_t* __restrict__ X, int ldx, int K, int nN, char* shm, const Epi& epi) {
;     ...
;   auto stage = [&](int buf, int n0, int m0, int kt) {
;     const char* wk = (const char*)(W + (size_t)n0 * ldw) + kt * 128;
;     const char* xk = (const char*)(X + (size_t)m0 * ldx) + kt * 128;
; #pragma unroll
;     for (int i = 0; i < 4; ++i) {
;       unsigned ow = offW[i], ox = offX[i];
;       asm volatile("" : "+v"(ow), "+v"(ox));
;       __builtin_amdgcn_global_load_lds((const unsigned*)(wk + ow), (unsigned*)(shm + buf * STAGE_B + wid * 1024 + i * 8192), 16, 0, 0);
;       __builtin_amdgcn_global_load_lds((const unsigned*)(xk + ox), (unsigned*)(shm + buf * STAGE_B + TILE_B + wid * 1024 + i * 8192), 16, 0, 0);
;     }
;     ...
;       for (int ks = 0; ks < 2; ++ks) {
;         const int kx = (wid >> 2) ? (1 - 2 * ks) * 1024 : 0;
;         bf16x8 At[8], Bf[4];
; #pragma unroll
;         for (int m = 0; m < 8; ++m) At[m] = *(const bf16x8*)(SAp + (2 * m + ks) * 1024 + kx);
; #pragma unroll
;         for (int n = 0; n < 4; ++n) Bf[n] = *(const bf16x8*)(SBp + (2 * n + ks) * 1024 + kx);
; #pragma unroll
;         for (int m = 0; m < 8; ++m)
; #pragma unroll
;           for (int n = 0; n < 4; ++n) acc[m][n] = mfma16(At[m], Bf[n], acc[m][n]);
;         __builtin_amdgcn_sched_barrier(0);
;         if (ks == 0 && wid >= 4) {
;           if (st_own) stage(cur ^ 1, n0, m0, kt0 + t + 1);
;           else if (st_next) stage(cur ^ 1, n1, m1, kt1);
;         }
.Lmy_xf_985:
	s_add_u32 s98, s12, s57
	s_addc_u32 s99, s13, 0
	s_add_u32 s98, s98, 0x80
	s_addc_u32 s99, s99, 0
	s_add_u32 s100, s55, s57
	s_addc_u32 s101, s56, 0
	s_add_u32 s100, s100, 0x80
	s_addc_u32 s101, s101, 0
	s_xor_b32 m0, s59, 0x10000
	s_add_i32 m0, m0, s14
	s_waitcnt lgkmcnt(2)
	v_mfma_f32_16x16x32_bf16 v[124:127], v[220:223], v[134:137], v[124:127]
	v_mfma_f32_16x16x32_bf16 v[120:123], v[220:223], v[142:145], v[120:123]
	v_mfma_f32_16x16x32_bf16 v[116:119], v[220:223], v[146:149], v[116:119]
	v_mfma_f32_16x16x32_bf16 v[112:115], v[220:223], v[150:153], v[112:115]
	global_load_lds_dwordx4 v194, s[98:99]
	ds_read_b128 v[236:239], v154 offset:8192
	s_add_i32 m0, m0, 0x8000
	s_waitcnt lgkmcnt(3)
	v_mfma_f32_16x16x32_bf16 v[108:111], v[224:227], v[134:137], v[108:111]
	v_mfma_f32_16x16x32_bf16 v[104:107], v[224:227], v[142:145], v[104:107]
	v_mfma_f32_16x16x32_bf16 v[100:103], v[224:227], v[146:149], v[100:103]
	v_mfma_f32_16x16x32_bf16 v[96:99], v[224:227], v[150:153], v[96:99]
	global_load_lds_dwordx4 v194, s[100:101]
	ds_read_b128 v[240:243], v154 offset:10240
	s_add_i32 m0, m0, 0xffffa000
	s_waitcnt lgkmcnt(3)
	v_mfma_f32_16x16x32_bf16 v[92:95], v[228:231], v[134:137], v[92:95]
	v_mfma_f32_16x16x32_bf16 v[88:91], v[228:231], v[142:145], v[88:91]
	v_mfma_f32_16x16x32_bf16 v[84:87], v[228:231], v[146:149], v[84:87]
	v_mfma_f32_16x16x32_bf16 v[80:83], v[228:231], v[150:153], v[80:83]
	global_load_lds_dwordx4 v195, s[98:99]
	ds_read_b128 v[244:247], v154 offset:12288
	s_add_i32 m0, m0, 0x8000
	s_waitcnt lgkmcnt(3)
	v_mfma_f32_16x16x32_bf16 v[76:79], v[232:235], v[134:137], v[76:79]
	v_mfma_f32_16x16x32_bf16 v[72:75], v[232:235], v[142:145], v[72:75]
	v_mfma_f32_16x16x32_bf16 v[68:71], v[232:235], v[146:149], v[68:71]
	v_mfma_f32_16x16x32_bf16 v[64:67], v[232:235], v[150:153], v[64:67]
	global_load_lds_dwordx4 v195, s[100:101]
	ds_read_b128 v[248:251], v154 offset:14336
	s_add_i32 m0, m0, 0xffffa000
	s_waitcnt lgkmcnt(3)
	v_mfma_f32_16x16x32_bf16 v[60:63], v[236:239], v[134:137], v[60:63]
	v_mfma_f32_16x16x32_bf16 v[56:59], v[236:239], v[142:145], v[56:59]
	v_mfma_f32_16x16x32_bf16 v[52:55], v[236:239], v[146:149], v[52:55]
	v_mfma_f32_16x16x32_bf16 v[48:51], v[236:239], v[150:153], v[48:51]
	global_load_lds_dwordx4 v196, s[98:99]
	s_add_i32 m0, m0, 0x8000
	s_waitcnt lgkmcnt(2)
	v_mfma_f32_16x16x32_bf16 v[44:47], v[240:243], v[134:137], v[44:47]
	v_mfma_f32_16x16x32_bf16 v[40:43], v[240:243], v[142:145], v[40:43]
	v_mfma_f32_16x16x32_bf16 v[36:39], v[240:243], v[146:149], v[36:39]
	v_mfma_f32_16x16x32_bf16 v[32:35], v[240:243], v[150:153], v[32:35]
	global_load_lds_dwordx4 v196, s[100:101]
	s_add_i32 m0, m0, 0xffffa000
	s_waitcnt lgkmcnt(0)
	v_add_u32_e32 v154, s42, v129
	v_add_u32_e32 v128, s42, v128
	s_add_i32 s58, s58, 1
	ds_read_b128 v[220:223], v154 offset:1024
	ds_read_b128 v[224:227], v154 offset:3072
	v_mfma_f32_16x16x32_bf16 v[28:31], v[244:247], v[134:137], v[28:31]
	v_mfma_f32_16x16x32_bf16 v[12:15], v[248:251], v[134:137], v[12:15]
	ds_read_b128 v[134:137], v128 offset:33792
	v_mfma_f32_16x16x32_bf16 v[24:27], v[244:247], v[142:145], v[24:27]
	v_mfma_f32_16x16x32_bf16 v[8:11], v[248:251], v[142:145], v[8:11]
	ds_read_b128 v[142:145], v128 offset:35840
	global_load_lds_dwordx4 v197, s[98:99]
	s_add_i32 m0, m0, 0x8000
	v_mfma_f32_16x16x32_bf16 v[20:23], v[244:247], v[146:149], v[20:23]
	v_mfma_f32_16x16x32_bf16 v[4:7], v[248:251], v[146:149], v[4:7]
	ds_read_b128 v[146:149], v128 offset:37888
	v_mfma_f32_16x16x32_bf16 v[16:19], v[244:247], v[150:153], v[16:19]
	v_mfma_f32_16x16x32_bf16 v[0:3], v[248:251], v[150:153], v[0:3]
	ds_read_b128 v[150:153], v128 offset:39936
	global_load_lds_dwordx4 v197, s[100:101]
	ds_read_b128 v[228:231], v154 offset:5120
	ds_read_b128 v[232:235], v154 offset:7168
	s_and_b64 vcc, exec, s[0:1]
	s_branch .Lmy_xs_985
	s_xor_b32 s10, s59, 0x10000
	s_add_i32 s59, s14, s10
	s_add_i32 s62, s59, 0xe000
	s_add_i32 s63, s59, 0x6000
	s_add_i32 s64, s59, 0xc000
	s_add_i32 s65, s59, 0x4000
	s_add_i32 s66, s59, 0xa000
	s_add_i32 s67, s59, 0x2000
	s_add_i32 s68, s59, 0x8000
	s_ashr_i32 s61, s57, 31
	s_add_u32 s10, s55, s57
	s_addc_u32 s11, s56, s61
	s_add_u32 s60, s12, s57
	s_addc_u32 s61, s13, s61
	v_mov_b32_e32 v192, v194
	v_mov_b32_e32 v130, v194
	v_mov_b32_e32 v131, v193
	v_lshl_add_u64 v[132:133], s[60:61], 0, v[192:193]
	v_lshl_add_u64 v[132:133], v[132:133], 0, s[6:7]
	s_mov_b32 m0, s59
	v_lshl_add_u64 v[130:131], s[10:11], 0, v[130:131]
	global_load_lds_dwordx4 v[132:133], off
	v_lshl_add_u64 v[130:131], v[130:131], 0, s[6:7]
	s_mov_b32 m0, s68
	v_mov_b32_e32 v192, v195
	global_load_lds_dwordx4 v[130:131], off
	v_mov_b32_e32 v130, v195
	v_mov_b32_e32 v131, v193
	v_lshl_add_u64 v[132:133], s[60:61], 0, v[192:193]
	v_lshl_add_u64 v[132:133], v[132:133], 0, s[6:7]
	s_mov_b32 m0, s67
	v_lshl_add_u64 v[130:131], s[10:11], 0, v[130:131]
	global_load_lds_dwordx4 v[132:133], off
	v_lshl_add_u64 v[130:131], v[130:131], 0, s[6:7]
	s_mov_b32 m0, s66
	v_mov_b32_e32 v192, v196
	global_load_lds_dwordx4 v[130:131], off
	v_mov_b32_e32 v130, v196
	v_mov_b32_e32 v131, v193
	v_lshl_add_u64 v[132:133], s[60:61], 0, v[192:193]
	v_lshl_add_u64 v[132:133], v[132:133], 0, s[6:7]
	s_mov_b32 m0, s65
	v_lshl_add_u64 v[130:131], s[10:11], 0, v[130:131]
	global_load_lds_dwordx4 v[132:133], off
	v_lshl_add_u64 v[130:131], v[130:131], 0, s[6:7]
	s_mov_b32 m0, s64
	v_mov_b32_e32 v192, v197
	global_load_lds_dwordx4 v[130:131], off
	v_mov_b32_e32 v130, v197
	v_mov_b32_e32 v131, v193
	v_lshl_add_u64 v[132:133], s[60:61], 0, v[192:193]
	v_lshl_add_u64 v[132:133], v[132:133], 0, s[6:7]
	s_mov_b32 m0, s63
	v_lshl_add_u64 v[130:131], s[10:11], 0, v[130:131]
	global_load_lds_dwordx4 v[132:133], off
	v_lshl_add_u64 v[130:131], v[130:131], 0, s[6:7]
	s_mov_b32 m0, s62
	s_nop 0
	global_load_lds_dwordx4 v[130:131], off
	s_branch .LBB0_984

; DEVI f32x4 mfma16(bf16x8 a, bf16x8 b, f32x4 c) { return __builtin_amdgcn_mfma_f32_16x16x32_bf16(a, b, c, 0, 0, 0); }
; template <int MODE, class Epi>
; DEVI void gemm256_phase(int sw, const bf16_t* __restrict__ W, int ldw, const bf16_t* __restrict__ X, int ldx, int K, int nN, char* shm, const Epi& epi) {
;     ...
;     for (int t = 0; t < ntk; ++t) {
;       const int cur = (b0 + t) & 1;
;       const bool st_own = t + 1 < ntk, st_next = !st_own && has_next;
;       if (wid < 4) {
;         if (st_own) stage(cur ^ 1, n0, m0, kt0 + t + 1);
;         else if (st_next) stage(cur ^ 1, n1, m1, kt1);
;       }
;       const char* SAp = shm + cur * STAGE_B + wr * (16 * 1024) + lds_lo;
;       const char* SBp = shm + cur * STAGE_B + TILE_B + wc * (8 * 1024) + lds_lo;
; #pragma unroll
;       for (int ks = 0; ks < 2; ++ks) {
;         const int kx = (wid >> 2) ? (1 - 2 * ks) * 1024 : 0;
;         bf16x8 At[8], Bf[4];
; #pragma unroll
;         for (int m = 0; m < 8; ++m) At[m] = *(const bf16x8*)(SAp + (2 * m + ks) * 1024 + kx);
; #pragma unroll
;         for (int n = 0; n < 4; ++n) Bf[n] = *(const bf16x8*)(SBp + (2 * n + ks) * 1024 + kx);
; #pragma unroll
;         for (int m = 0; m < 8; ++m)
; #pragma unroll
;           for (int n = 0; n < 4; ++n) acc[m][n] = mfma16(At[m], Bf[n], acc[m][n]);
;         __builtin_amdgcn_sched_barrier(0);
;         if (ks == 0 && wid >= 4) {
;           if (st_own) stage(cur ^ 1, n0, m0, kt0 + t + 1);
;           else if (st_next) stage(cur ^ 1, n1, m1, kt1);
;         }
;       }
;       asm volatile("s_waitcnt vmcnt(0)" ::: "memory");
;       __syncthreads();
;     }
.LBB0_1033:
.Lmy_xs_1034:
	s_waitcnt lgkmcnt(2)
	v_mfma_f32_16x16x32_bf16 v[124:127], v[220:223], v[134:137], v[124:127]
	v_mfma_f32_16x16x32_bf16 v[120:123], v[220:223], v[142:145], v[120:123]
	v_mfma_f32_16x16x32_bf16 v[116:119], v[220:223], v[146:149], v[116:119]
	v_mfma_f32_16x16x32_bf16 v[112:115], v[220:223], v[150:153], v[112:115]
	ds_read_b128 v[236:239], v154 offset:9216
	s_waitcnt lgkmcnt(3)
	v_mfma_f32_16x16x32_bf16 v[108:111], v[224:227], v[134:137], v[108:111]
	v_mfma_f32_16x16x32_bf16 v[104:107], v[224:227], v[142:145], v[104:107]
	v_mfma_f32_16x16x32_bf16 v[100:103], v[224:227], v[146:149], v[100:103]
	v_mfma_f32_16x16x32_bf16 v[96:99], v[224:227], v[150:153], v[96:99]
	ds_read_b128 v[240:243], v154 offset:11264
	s_waitcnt lgkmcnt(3)
	v_mfma_f32_16x16x32_bf16 v[92:95], v[228:231], v[134:137], v[92:95]
	v_mfma_f32_16x16x32_bf16 v[88:91], v[228:231], v[142:145], v[88:91]
	v_mfma_f32_16x16x32_bf16 v[84:87], v[228:231], v[146:149], v[84:87]
	v_mfma_f32_16x16x32_bf16 v[80:83], v[228:231], v[150:153], v[80:83]
	ds_read_b128 v[244:247], v154 offset:13312
	s_waitcnt lgkmcnt(3)
	v_mfma_f32_16x16x32_bf16 v[76:79], v[232:235], v[134:137], v[76:79]
	v_mfma_f32_16x16x32_bf16 v[72:75], v[232:235], v[142:145], v[72:75]
	v_mfma_f32_16x16x32_bf16 v[68:71], v[232:235], v[146:149], v[68:71]
	v_mfma_f32_16x16x32_bf16 v[64:67], v[232:235], v[150:153], v[64:67]
	ds_read_b128 v[248:251], v154 offset:15360
	s_waitcnt lgkmcnt(3)
	v_mfma_f32_16x16x32_bf16 v[60:63], v[236:239], v[134:137], v[60:63]
	v_mfma_f32_16x16x32_bf16 v[56:59], v[236:239], v[142:145], v[56:59]
	v_mfma_f32_16x16x32_bf16 v[52:55], v[236:239], v[146:149], v[52:55]
	v_mfma_f32_16x16x32_bf16 v[48:51], v[236:239], v[150:153], v[48:51]
	s_waitcnt lgkmcnt(2)
	v_mfma_f32_16x16x32_bf16 v[44:47], v[240:243], v[134:137], v[44:47]
	v_mfma_f32_16x16x32_bf16 v[40:43], v[240:243], v[142:145], v[40:43]
	v_mfma_f32_16x16x32_bf16 v[36:39], v[240:243], v[146:149], v[36:39]
	v_mfma_f32_16x16x32_bf16 v[32:35], v[240:243], v[150:153], v[32:35]
	s_addk_i32 s81, 0x80
	s_cmp_eq_u32 s80, s82
	s_cbranch_scc1 .Lmy_xexit_1034
	s_add_i32 s0, s61, s82
	s_and_b32 s83, s0, 1
	s_add_i32 s82, s82, 1
	s_cmp_lt_i32 s82, s54
	s_cselect_b64 s[0:1], -1, 0
	s_cmp_ge_i32 s82, s54
	s_cselect_b64 s[40:41], -1, 0
	v_cmp_ne_u32_e32 vcc, 1, v197
	v_cndmask_b32_e64 v128, 0, 1, s[0:1]
	s_and_b64 s[40:41], s[38:39], s[40:41]
	v_cmp_ne_u32_e64 s[0:1], 1, v128
	s_lshl_b32 s42, s83, 16
	s_add_i32 s43, s42, s58
	v_add_u32_e32 v129, s43, v194
	v_add_u32_e32 v253, s62, v129
	s_or_b32 s43, s42, s59
	v_add_u32_e32 v128, s43, v194
	v_add_u32_e32 v252, s62, v128
	s_waitcnt lgkmcnt(0)
	s_waitcnt vmcnt(0)
	s_barrier
	ds_read_b128 v[220:223], v253
	ds_read_b128 v[224:227], v253 offset:2048
	v_mfma_f32_16x16x32_bf16 v[28:31], v[244:247], v[134:137], v[28:31]
	v_mfma_f32_16x16x32_bf16 v[12:15], v[248:251], v[134:137], v[12:15]
	ds_read_b128 v[134:137], v252 offset:32768
	v_mfma_f32_16x16x32_bf16 v[24:27], v[244:247], v[142:145], v[24:27]
	v_mfma_f32_16x16x32_bf16 v[8:11], v[248:251], v[142:145], v[8:11]
	ds_read_b128 v[142:145], v252 offset:34816
	v_mfma_f32_16x16x32_bf16 v[20:23], v[244:247], v[146:149], v[20:23]
	v_mfma_f32_16x16x32_bf16 v[4:7], v[248:251], v[146:149], v[4:7]
	ds_read_b128 v[146:149], v252 offset:36864
	v_mfma_f32_16x16x32_bf16 v[16:19], v[244:247], v[150:153], v[16:19]
	v_mfma_f32_16x16x32_bf16 v[0:3], v[248:251], v[150:153], v[0:3]
	ds_read_b128 v[150:153], v252 offset:38912
	ds_read_b128 v[228:231], v253 offset:4096
	ds_read_b128 v[232:235], v253 offset:6144
	v_mov_b32_e32 v154, v253
	s_branch .Lmy_xf_1034

; DEVI f32x4 mfma16(bf16x8 a, bf16x8 b, f32x4 c) { return __builtin_amdgcn_mfma_f32_16x16x32_bf16(a, b, c, 0, 0, 0); }
; template <int MODE, class Epi>
; DEVI void gemm256_phase(int sw, const bf16_t* __restrict__ W, int ldw, const bf16_t* __restrict__ X, int ldx, int K, int nN, char* shm, const Epi& epi) {
;     ...
;   auto stage = [&](int buf, int n0, int m0, int kt) {
;     const char* wk = (const char*)(W + (size_t)n0 * ldw) + kt * 128;
;     const char* xk = (const char*)(X + (size_t)m0 * ldx) + kt * 128;
; #pragma unroll
;     for (int i = 0; i < 4; ++i) {
;       unsigned ow = offW[i], ox = offX[i];
;       asm volatile("" : "+v"(ow), "+v"(ox));
;       __builtin_amdgcn_global_load_lds((const unsigned*)(wk + ow), (unsigned*)(shm + buf * STAGE_B + wid * 1024 + i * 8192), 16, 0, 0);
;       __builtin_amdgcn_global_load_lds((const unsigned*)(xk + ox), (unsigned*)(shm + buf * STAGE_B + TILE_B + wid * 1024 + i * 8192), 16, 0, 0);
;     }
;     ...
;       for (int ks = 0; ks < 2; ++ks) {
;         const int kx = (wid >> 2) ? (1 - 2 * ks) * 1024 : 0;
;         bf16x8 At[8], Bf[4];
; #pragma unroll
;         for (int m = 0; m < 8; ++m) At[m] = *(const bf16x8*)(SAp + (2 * m + ks) * 1024 + kx);
; #pragma unroll
;         for (int n = 0; n < 4; ++n) Bf[n] = *(const bf16x8*)(SBp + (2 * n + ks) * 1024 + kx);
; #pragma unroll
;         for (int m = 0; m < 8; ++m)
; #pragma unroll
;           for (int n = 0; n < 4; ++n) acc[m][n] = mfma16(At[m], Bf[n], acc[m][n]);
;         __builtin_amdgcn_sched_barrier(0);
;         if (ks == 0 && wid >= 4) {
;           if (st_own) stage(cur ^ 1, n0, m0, kt0 + t + 1);
;           else if (st_next) stage(cur ^ 1, n1, m1, kt1);
;         }
.Lmy_xf_1034:
	s_add_u32 s98, s78, s81
	s_addc_u32 s99, s79, 0
	s_add_u32 s98, s98, 0x80
	s_addc_u32 s99, s99, 0
	s_add_u32 s100, s76, s81
	s_addc_u32 s101, s77, 0
	s_add_u32 s100, s100, 0x80
	s_addc_u32 s101, s101, 0
	s_xor_b32 m0, s42, 0x10000
	s_add_i32 m0, m0, s57
	s_waitcnt lgkmcnt(2)
	v_mfma_f32_16x16x32_bf16 v[124:127], v[220:223], v[134:137], v[124:127]
	v_mfma_f32_16x16x32_bf16 v[120:123], v[220:223], v[142:145], v[120:123]
	v_mfma_f32_16x16x32_bf16 v[116:119], v[220:223], v[146:149], v[116:119]
	v_mfma_f32_16x16x32_bf16 v[112:115], v[220:223], v[150:153], v[112:115]
	global_load_lds_dwordx4 v190, s[98:99]
	ds_read_b128 v[236:239], v154 offset:8192
	s_add_i32 m0, m0, 0x8000
	s_waitcnt lgkmcnt(3)
	v_mfma_f32_16x16x32_bf16 v[108:111], v[224:227], v[134:137], v[108:111]
	v_mfma_f32_16x16x32_bf16 v[104:107], v[224:227], v[142:145], v[104:107]
	v_mfma_f32_16x16x32_bf16 v[100:103], v[224:227], v[146:149], v[100:103]
	v_mfma_f32_16x16x32_bf16 v[96:99], v[224:227], v[150:153], v[96:99]
	global_load_lds_dwordx4 v190, s[100:101]
	ds_read_b128 v[240:243], v154 offset:10240
	s_add_i32 m0, m0, 0xffffa000
	s_waitcnt lgkmcnt(3)
	v_mfma_f32_16x16x32_bf16 v[92:95], v[228:231], v[134:137], v[92:95]
	v_mfma_f32_16x16x32_bf16 v[88:91], v[228:231], v[142:145], v[88:91]
	v_mfma_f32_16x16x32_bf16 v[84:87], v[228:231], v[146:149], v[84:87]
	v_mfma_f32_16x16x32_bf16 v[80:83], v[228:231], v[150:153], v[80:83]
	global_load_lds_dwordx4 v191, s[98:99]
	ds_read_b128 v[244:247], v154 offset:12288
	s_add_i32 m0, m0, 0x8000
	s_waitcnt lgkmcnt(3)
	v_mfma_f32_16x16x32_bf16 v[76:79], v[232:235], v[134:137], v[76:79]
	v_mfma_f32_16x16x32_bf16 v[72:75], v[232:235], v[142:145], v[72:75]
	v_mfma_f32_16x16x32_bf16 v[68:71], v[232:235], v[146:149], v[68:71]
	v_mfma_f32_16x16x32_bf16 v[64:67], v[232:235], v[150:153], v[64:67]
	global_load_lds_dwordx4 v191, s[100:101]
	ds_read_b128 v[248:251], v154 offset:14336
	s_add_i32 m0, m0, 0xffffa000
	s_waitcnt lgkmcnt(3)
	v_mfma_f32_16x16x32_bf16 v[60:63], v[236:239], v[134:137], v[60:63]
	v_mfma_f32_16x16x32_bf16 v[56:59], v[236:239], v[142:145], v[56:59]
	v_mfma_f32_16x16x32_bf16 v[52:55], v[236:239], v[146:149], v[52:55]
	v_mfma_f32_16x16x32_bf16 v[48:51], v[236:239], v[150:153], v[48:51]
	global_load_lds_dwordx4 v192, s[98:99]
	s_add_i32 m0, m0, 0x8000
	s_waitcnt lgkmcnt(2)
	v_mfma_f32_16x16x32_bf16 v[44:47], v[240:243], v[134:137], v[44:47]
	v_mfma_f32_16x16x32_bf16 v[40:43], v[240:243], v[142:145], v[40:43]
	v_mfma_f32_16x16x32_bf16 v[36:39], v[240:243], v[146:149], v[36:39]
	v_mfma_f32_16x16x32_bf16 v[32:35], v[240:243], v[150:153], v[32:35]
	global_load_lds_dwordx4 v192, s[100:101]
	s_add_i32 m0, m0, 0xffffa000
	s_waitcnt lgkmcnt(0)
	v_add_u32_e32 v154, s63, v129
	v_add_u32_e32 v128, s63, v128
	ds_read_b128 v[220:223], v154 offset:1024
	ds_read_b128 v[224:227], v154 offset:3072
	v_mfma_f32_16x16x32_bf16 v[28:31], v[244:247], v[134:137], v[28:31]
	v_mfma_f32_16x16x32_bf16 v[12:15], v[248:251], v[134:137], v[12:15]
	ds_read_b128 v[134:137], v128 offset:33792
	v_mfma_f32_16x16x32_bf16 v[24:27], v[244:247], v[142:145], v[24:27]
	v_mfma_f32_16x16x32_bf16 v[8:11], v[248:251], v[142:145], v[8:11]
	ds_read_b128 v[142:145], v128 offset:35840
	global_load_lds_dwordx4 v193, s[98:99]
	s_add_i32 m0, m0, 0x8000
	v_mfma_f32_16x16x32_bf16 v[20:23], v[244:247], v[146:149], v[20:23]
	v_mfma_f32_16x16x32_bf16 v[4:7], v[248:251], v[146:149], v[4:7]
	ds_read_b128 v[146:149], v128 offset:37888
	v_mfma_f32_16x16x32_bf16 v[16:19], v[244:247], v[150:153], v[16:19]
	v_mfma_f32_16x16x32_bf16 v[0:3], v[248:251], v[150:153], v[0:3]
	ds_read_b128 v[150:153], v128 offset:39936
	global_load_lds_dwordx4 v193, s[100:101]
	ds_read_b128 v[228:231], v154 offset:5120
	ds_read_b128 v[232:235], v154 offset:7168
	s_andn2_b64 vcc, exec, s[8:9]
	s_branch .Lmy_xs_1034
	s_and_b64 vcc, exec, s[0:1]
	s_xor_b32 s52, s42, 0x10000
	s_cbranch_vccnz .LBB0_1046
	s_ashr_i32 s42, s81, 31
	s_add_u32 s44, s78, s81
	s_addc_u32 s45, s79, s42
	s_add_u32 s0, s44, 0x80
	s_addc_u32 s1, s45, 0
	s_add_u32 s46, s76, s81
	s_addc_u32 s47, s77, s42
	s_add_u32 s42, s46, 0x80
	v_mov_b32_e32 v188, v190
	v_mov_b32_e32 v130, v190
	s_addc_u32 s43, s47, 0
	s_add_i32 s53, s57, s52
	v_lshl_add_u64 v[132:133], s[44:45], 0, v[188:189]
	v_mov_b32_e32 v131, v189
	v_lshl_add_u64 v[132:133], v[132:133], 0, s[10:11]
	s_mov_b32 m0, s53
	v_lshl_add_u64 v[130:131], s[46:47], 0, v[130:131]
	global_load_lds_dwordx4 v[132:133], off
	v_lshl_add_u64 v[130:131], v[130:131], 0, s[10:11]
	s_add_i32 m0, s53, 0x8000
	v_mov_b32_e32 v188, v191
	global_load_lds_dwordx4 v[130:131], off
	v_mov_b32_e32 v130, v191
	v_mov_b32_e32 v131, v189
	v_lshl_add_u64 v[132:133], s[44:45], 0, v[188:189]
	v_lshl_add_u64 v[132:133], v[132:133], 0, s[10:11]
	s_add_i32 m0, s53, 0x2000
	v_lshl_add_u64 v[130:131], s[46:47], 0, v[130:131]
	global_load_lds_dwordx4 v[132:133], off
	v_lshl_add_u64 v[130:131], v[130:131], 0, s[10:11]
	s_add_i32 m0, s53, 0xa000
	v_mov_b32_e32 v188, v192
	global_load_lds_dwordx4 v[130:131], off
	v_mov_b32_e32 v130, v192
	v_mov_b32_e32 v131, v189
	v_lshl_add_u64 v[132:133], s[44:45], 0, v[188:189]
	v_lshl_add_u64 v[132:133], v[132:133], 0, s[10:11]
	s_add_i32 m0, s53, 0x4000
	v_lshl_add_u64 v[130:131], s[46:47], 0, v[130:131]
	global_load_lds_dwordx4 v[132:133], off
	v_lshl_add_u64 v[130:131], v[130:131], 0, s[10:11]
	s_add_i32 m0, s53, 0xc000
	s_nop 0
	global_load_lds_dwordx4 v[130:131], off
	v_mov_b32_e32 v130, v193
	v_mov_b32_e32 v131, v193
	s_mov_b64 s[44:45], -1
	s_cbranch_execz .LBB0_1047
	s_branch .LBB0_1050

; DEVI f32x4 mfma16(bf16x8 a, bf16x8 b, f32x4 c) { return __builtin_amdgcn_mfma_f32_16x16x32_bf16(a, b, c, 0, 0, 0); }
; template <int MODE, class Epi>
; DEVI void gemm256_phase(int sw, const bf16_t* __restrict__ W, int ldw, const bf16_t* __restrict__ X, int ldx, int K, int nN, char* shm, const Epi& epi) {
;     ...
; #pragma unroll
;       for (int ks = 0; ks < 2; ++ks) {
;         const int kx = (wid >> 2) ? (1 - 2 * ks) * 1024 : 0;
;         bf16x8 At[8], Bf[4];
; #pragma unroll
;         for (int m = 0; m < 8; ++m) At[m] = *(const bf16x8*)(SAp + (2 * m + ks) * 1024 + kx);
; #pragma unroll
;         for (int n = 0; n < 4; ++n) Bf[n] = *(const bf16x8*)(SBp + (2 * n + ks) * 1024 + kx);
; #pragma unroll
;         for (int m = 0; m < 8; ++m)
; #pragma unroll
;           for (int n = 0; n < 4; ++n) acc[m][n] = mfma16(At[m], Bf[n], acc[m][n]);
;         __builtin_amdgcn_sched_barrier(0);
;         if (ks == 0 && wid >= 4) {
;           if (st_own) stage(cur ^ 1, n0, m0, kt0 + t + 1);
;           else if (st_next) stage(cur ^ 1, n1, m1, kt1);
;         }
;       }
;       asm volatile("s_waitcnt vmcnt(0)" ::: "memory");
;       __syncthreads();
.LBB0_1269:
.Lmy_xs_1270:
	s_waitcnt lgkmcnt(2)
	v_mfma_f32_16x16x32_bf16 v[124:127], v[220:223], v[134:137], v[124:127]
	v_mfma_f32_16x16x32_bf16 v[120:123], v[220:223], v[142:145], v[120:123]
	v_mfma_f32_16x16x32_bf16 v[116:119], v[220:223], v[146:149], v[116:119]
	v_mfma_f32_16x16x32_bf16 v[112:115], v[220:223], v[150:153], v[112:115]
	ds_read_b128 v[236:239], v154 offset:9216
	s_waitcnt lgkmcnt(3)
	v_mfma_f32_16x16x32_bf16 v[108:111], v[224:227], v[134:137], v[108:111]
	v_mfma_f32_16x16x32_bf16 v[104:107], v[224:227], v[142:145], v[104:107]
	v_mfma_f32_16x16x32_bf16 v[100:103], v[224:227], v[146:149], v[100:103]
	v_mfma_f32_16x16x32_bf16 v[96:99], v[224:227], v[150:153], v[96:99]
	ds_read_b128 v[240:243], v154 offset:11264
	s_waitcnt lgkmcnt(3)
	v_mfma_f32_16x16x32_bf16 v[92:95], v[228:231], v[134:137], v[92:95]
	v_mfma_f32_16x16x32_bf16 v[88:91], v[228:231], v[142:145], v[88:91]
	v_mfma_f32_16x16x32_bf16 v[84:87], v[228:231], v[146:149], v[84:87]
	v_mfma_f32_16x16x32_bf16 v[80:83], v[228:231], v[150:153], v[80:83]
	ds_read_b128 v[244:247], v154 offset:13312
	s_waitcnt lgkmcnt(3)
	v_mfma_f32_16x16x32_bf16 v[76:79], v[232:235], v[134:137], v[76:79]
	v_mfma_f32_16x16x32_bf16 v[72:75], v[232:235], v[142:145], v[72:75]
	v_mfma_f32_16x16x32_bf16 v[68:71], v[232:235], v[146:149], v[68:71]
	v_mfma_f32_16x16x32_bf16 v[64:67], v[232:235], v[150:153], v[64:67]
	ds_read_b128 v[248:251], v154 offset:15360
	s_waitcnt lgkmcnt(3)
	v_mfma_f32_16x16x32_bf16 v[60:63], v[236:239], v[134:137], v[60:63]
	v_mfma_f32_16x16x32_bf16 v[56:59], v[236:239], v[142:145], v[56:59]
	v_mfma_f32_16x16x32_bf16 v[52:55], v[236:239], v[146:149], v[52:55]
	v_mfma_f32_16x16x32_bf16 v[48:51], v[236:239], v[150:153], v[48:51]
	s_waitcnt lgkmcnt(2)
	v_mfma_f32_16x16x32_bf16 v[44:47], v[240:243], v[134:137], v[44:47]
	v_mfma_f32_16x16x32_bf16 v[40:43], v[240:243], v[142:145], v[40:43]
	v_mfma_f32_16x16x32_bf16 v[36:39], v[240:243], v[146:149], v[36:39]
	v_mfma_f32_16x16x32_bf16 v[32:35], v[240:243], v[150:153], v[32:35]
	s_addk_i32 s72, 0x80
	s_cmp_eq_u32 s71, s73
	s_cbranch_scc1 .Lmy_xexit_1270
	s_add_i32 s0, s49, s73
	s_and_b32 s74, s0, 1
	s_add_i32 s73, s73, 1
	s_cmp_lt_i32 s73, s54
	s_cselect_b64 s[0:1], -1, 0
	s_cmp_ge_i32 s73, s54
	s_cselect_b64 s[8:9], -1, 0
	v_cndmask_b32_e64 v128, 0, 1, s[0:1]
	s_and_b64 s[8:9], s[2:3], s[8:9]
	s_andn2_b64 vcc, exec, s[40:41]
	v_cmp_ne_u32_e64 s[0:1], 1, v128
	s_lshl_b32 s10, s74, 16
	s_add_i32 s11, s10, s55
	v_add_u32_e32 v129, s11, v194
	v_add_u32_e32 v253, s57, v129
	s_or_b32 s11, s10, s56
	v_add_u32_e32 v128, s11, v194
	v_add_u32_e32 v252, s57, v128
	s_waitcnt lgkmcnt(0)
	s_waitcnt vmcnt(0)
	s_barrier
	ds_read_b128 v[220:223], v253
	ds_read_b128 v[224:227], v253 offset:2048
	v_mfma_f32_16x16x32_bf16 v[28:31], v[244:247], v[134:137], v[28:31]
	v_mfma_f32_16x16x32_bf16 v[12:15], v[248:251], v[134:137], v[12:15]
	ds_read_b128 v[134:137], v252 offset:32768
	v_mfma_f32_16x16x32_bf16 v[24:27], v[244:247], v[142:145], v[24:27]
	v_mfma_f32_16x16x32_bf16 v[8:11], v[248:251], v[142:145], v[8:11]
	ds_read_b128 v[142:145], v252 offset:34816
	v_mfma_f32_16x16x32_bf16 v[20:23], v[244:247], v[146:149], v[20:23]
	v_mfma_f32_16x16x32_bf16 v[4:7], v[248:251], v[146:149], v[4:7]
	ds_read_b128 v[146:149], v252 offset:36864
	v_mfma_f32_16x16x32_bf16 v[16:19], v[244:247], v[150:153], v[16:19]
	v_mfma_f32_16x16x32_bf16 v[0:3], v[248:251], v[150:153], v[0:3]
	ds_read_b128 v[150:153], v252 offset:38912
	ds_read_b128 v[228:231], v253 offset:4096
	ds_read_b128 v[232:235], v253 offset:6144
	v_mov_b32_e32 v154, v253
	s_branch .Lmy_xf_1270

; DEVI f32x4 mfma16(bf16x8 a, bf16x8 b, f32x4 c) { return __builtin_amdgcn_mfma_f32_16x16x32_bf16(a, b, c, 0, 0, 0); }
; template <int MODE, class Epi>
; DEVI void gemm256_phase(int sw, const bf16_t* __restrict__ W, int ldw, const bf16_t* __restrict__ X, int ldx, int K, int nN, char* shm, const Epi& epi) {
;     ...
;   auto stage = [&](int buf, int n0, int m0, int kt) {
;     const char* wk = (const char*)(W + (size_t)n0 * ldw) + kt * 128;
;     const char* xk = (const char*)(X + (size_t)m0 * ldx) + kt * 128;
; #pragma unroll
;     for (int i = 0; i < 4; ++i) {
;       unsigned ow = offW[i], ox = offX[i];
;       asm volatile("" : "+v"(ow), "+v"(ox));
;       __builtin_amdgcn_global_load_lds((const unsigned*)(wk + ow), (unsigned*)(shm + buf * STAGE_B + wid * 1024 + i * 8192), 16, 0, 0);
;       __builtin_amdgcn_global_load_lds((const unsigned*)(xk + ox), (unsigned*)(shm + buf * STAGE_B + TILE_B + wid * 1024 + i * 8192), 16, 0, 0);
;     }
;     ...
; #pragma unroll
;       for (int ks = 0; ks < 2; ++ks) {
;         const int kx = (wid >> 2) ? (1 - 2 * ks) * 1024 : 0;
;         bf16x8 At[8], Bf[4];
; #pragma unroll
;         for (int m = 0; m < 8; ++m) At[m] = *(const bf16x8*)(SAp + (2 * m + ks) * 1024 + kx);
; #pragma unroll
;         for (int n = 0; n < 4; ++n) Bf[n] = *(const bf16x8*)(SBp + (2 * n + ks) * 1024 + kx);
; #pragma unroll
;         for (int m = 0; m < 8; ++m)
; #pragma unroll
;           for (int n = 0; n < 4; ++n) acc[m][n] = mfma16(At[m], Bf[n], acc[m][n]);
;         __builtin_amdgcn_sched_barrier(0);
;         if (ks == 0 && wid >= 4) {
;           if (st_own) stage(cur ^ 1, n0, m0, kt0 + t + 1);
;           else if (st_next) stage(cur ^ 1, n1, m1, kt1);
;         }
.Lmy_xf_1270:
	s_add_u32 s98, s67, s72
	s_addc_u32 s99, s68, 0
	s_add_u32 s98, s98, 0x80
	s_addc_u32 s99, s99, 0
	s_add_u32 s100, s69, s72
	s_addc_u32 s101, s70, 0
	s_add_u32 s100, s100, 0x80
	s_addc_u32 s101, s101, 0
	s_xor_b32 m0, s10, 0x10000
	s_add_i32 m0, m0, s48
	s_waitcnt lgkmcnt(2)
	v_mfma_f32_16x16x32_bf16 v[124:127], v[220:223], v[134:137], v[124:127]
	v_mfma_f32_16x16x32_bf16 v[120:123], v[220:223], v[142:145], v[120:123]
	v_mfma_f32_16x16x32_bf16 v[116:119], v[220:223], v[146:149], v[116:119]
	v_mfma_f32_16x16x32_bf16 v[112:115], v[220:223], v[150:153], v[112:115]
	global_load_lds_dwordx4 v190, s[98:99]
	ds_read_b128 v[236:239], v154 offset:8192
	s_add_i32 m0, m0, 0x8000
	s_waitcnt lgkmcnt(3)
	v_mfma_f32_16x16x32_bf16 v[108:111], v[224:227], v[134:137], v[108:111]
	v_mfma_f32_16x16x32_bf16 v[104:107], v[224:227], v[142:145], v[104:107]
	v_mfma_f32_16x16x32_bf16 v[100:103], v[224:227], v[146:149], v[100:103]
	v_mfma_f32_16x16x32_bf16 v[96:99], v[224:227], v[150:153], v[96:99]
	global_load_lds_dwordx4 v190, s[100:101]
	ds_read_b128 v[240:243], v154 offset:10240
	s_add_i32 m0, m0, 0xffffa000
	s_waitcnt lgkmcnt(3)
	v_mfma_f32_16x16x32_bf16 v[92:95], v[228:231], v[134:137], v[92:95]
	v_mfma_f32_16x16x32_bf16 v[88:91], v[228:231], v[142:145], v[88:91]
	v_mfma_f32_16x16x32_bf16 v[84:87], v[228:231], v[146:149], v[84:87]
	v_mfma_f32_16x16x32_bf16 v[80:83], v[228:231], v[150:153], v[80:83]
	global_load_lds_dwordx4 v191, s[98:99]
	ds_read_b128 v[244:247], v154 offset:12288
	s_add_i32 m0, m0, 0x8000
	s_waitcnt lgkmcnt(3)
	v_mfma_f32_16x16x32_bf16 v[76:79], v[232:235], v[134:137], v[76:79]
	v_mfma_f32_16x16x32_bf16 v[72:75], v[232:235], v[142:145], v[72:75]
	v_mfma_f32_16x16x32_bf16 v[68:71], v[232:235], v[146:149], v[68:71]
	v_mfma_f32_16x16x32_bf16 v[64:67], v[232:235], v[150:153], v[64:67]
	global_load_lds_dwordx4 v191, s[100:101]
	ds_read_b128 v[248:251], v154 offset:14336
	s_add_i32 m0, m0, 0xffffa000
	s_waitcnt lgkmcnt(3)
	v_mfma_f32_16x16x32_bf16 v[60:63], v[236:239], v[134:137], v[60:63]
	v_mfma_f32_16x16x32_bf16 v[56:59], v[236:239], v[142:145], v[56:59]
	v_mfma_f32_16x16x32_bf16 v[52:55], v[236:239], v[146:149], v[52:55]
	v_mfma_f32_16x16x32_bf16 v[48:51], v[236:239], v[150:153], v[48:51]
	global_load_lds_dwordx4 v192, s[98:99]
	s_add_i32 m0, m0, 0x8000
	s_waitcnt lgkmcnt(2)
	v_mfma_f32_16x16x32_bf16 v[44:47], v[240:243], v[134:137], v[44:47]
	v_mfma_f32_16x16x32_bf16 v[40:43], v[240:243], v[142:145], v[40:43]
	v_mfma_f32_16x16x32_bf16 v[36:39], v[240:243], v[146:149], v[36:39]
	v_mfma_f32_16x16x32_bf16 v[32:35], v[240:243], v[150:153], v[32:35]
	global_load_lds_dwordx4 v192, s[100:101]
	s_add_i32 m0, m0, 0xffffa000
	s_waitcnt lgkmcnt(0)
	v_add_u32_e32 v154, s58, v129
	v_add_u32_e32 v128, s58, v128
	ds_read_b128 v[220:223], v154 offset:1024
	ds_read_b128 v[224:227], v154 offset:3072
	v_mfma_f32_16x16x32_bf16 v[28:31], v[244:247], v[134:137], v[28:31]
	v_mfma_f32_16x16x32_bf16 v[12:15], v[248:251], v[134:137], v[12:15]
	ds_read_b128 v[134:137], v128 offset:33792
	v_mfma_f32_16x16x32_bf16 v[24:27], v[244:247], v[142:145], v[24:27]
	v_mfma_f32_16x16x32_bf16 v[8:11], v[248:251], v[142:145], v[8:11]
	ds_read_b128 v[142:145], v128 offset:35840
	global_load_lds_dwordx4 v193, s[98:99]
	s_add_i32 m0, m0, 0x8000
	v_mfma_f32_16x16x32_bf16 v[20:23], v[244:247], v[146:149], v[20:23]
	v_mfma_f32_16x16x32_bf16 v[4:7], v[248:251], v[146:149], v[4:7]
	ds_read_b128 v[146:149], v128 offset:37888
	v_mfma_f32_16x16x32_bf16 v[16:19], v[244:247], v[150:153], v[16:19]
	v_mfma_f32_16x16x32_bf16 v[0:3], v[248:251], v[150:153], v[0:3]
	ds_read_b128 v[150:153], v128 offset:39936
	global_load_lds_dwordx4 v193, s[100:101]
	ds_read_b128 v[228:231], v154 offset:5120
	ds_read_b128 v[232:235], v154 offset:7168
	s_andn2_b64 vcc, exec, s[38:39]
	s_branch .Lmy_xs_1270
	s_and_b64 vcc, exec, s[0:1]
	s_xor_b32 s46, s10, 0x10000
	s_cbranch_vccnz .LBB0_1282
	s_ashr_i32 s10, s72, 31
	s_add_u32 s12, s67, s72
	s_addc_u32 s13, s68, s10
	s_add_u32 s0, s12, 0x80
	s_addc_u32 s1, s13, 0
	s_add_u32 s14, s69, s72
	s_addc_u32 s15, s70, s10
	s_add_u32 s10, s14, 0x80
	v_mov_b32_e32 v130, v190
	v_mov_b32_e32 v188, v190
	s_addc_u32 s11, s15, 0
	s_add_i32 s47, s48, s46
	v_lshl_add_u64 v[132:133], s[12:13], 0, v[188:189]
	v_mov_b32_e32 v131, v189
	v_lshl_add_u64 v[132:133], v[132:133], 0, s[42:43]
	s_mov_b32 m0, s47
	v_lshl_add_u64 v[130:131], s[14:15], 0, v[130:131]
	global_load_lds_dwordx4 v[132:133], off
	v_lshl_add_u64 v[130:131], v[130:131], 0, s[42:43]
	s_add_i32 m0, s47, 0x8000
	v_mov_b32_e32 v188, v191
	global_load_lds_dwordx4 v[130:131], off
	v_mov_b32_e32 v130, v191
	v_mov_b32_e32 v131, v189
	v_lshl_add_u64 v[132:133], s[12:13], 0, v[188:189]
	v_lshl_add_u64 v[132:133], v[132:133], 0, s[42:43]
	s_add_i32 m0, s47, 0x2000
	v_lshl_add_u64 v[130:131], s[14:15], 0, v[130:131]
	global_load_lds_dwordx4 v[132:133], off
	v_lshl_add_u64 v[130:131], v[130:131], 0, s[42:43]
	s_add_i32 m0, s47, 0xa000
	v_mov_b32_e32 v188, v192
	global_load_lds_dwordx4 v[130:131], off
	v_mov_b32_e32 v130, v192
	v_mov_b32_e32 v131, v189
	v_lshl_add_u64 v[132:133], s[12:13], 0, v[188:189]
	v_lshl_add_u64 v[132:133], v[132:133], 0, s[42:43]
	s_add_i32 m0, s47, 0x4000
	v_lshl_add_u64 v[130:131], s[14:15], 0, v[130:131]
	global_load_lds_dwordx4 v[132:133], off
	v_lshl_add_u64 v[130:131], v[130:131], 0, s[42:43]
	s_add_i32 m0, s47, 0xc000
	s_nop 0
	global_load_lds_dwordx4 v[130:131], off
	v_mov_b32_e32 v130, v193
	v_mov_b32_e32 v131, v193
	s_mov_b64 s[12:13], -1
	s_cbranch_execz .LBB0_1283
	s_branch .LBB0_1286

; DEVI f32x4 mfma16(bf16x8 a, bf16x8 b, f32x4 c) { return __builtin_amdgcn_mfma_f32_16x16x32_bf16(a, b, c, 0, 0, 0); }
; template <int MODE, class Epi>
; DEVI void gemm256_phase(int sw, const bf16_t* __restrict__ W, int ldw, const bf16_t* __restrict__ X, int ldx, int K, int nN, char* shm, const Epi& epi) {
;     ...
; #pragma unroll
;       for (int ks = 0; ks < 2; ++ks) {
;         const int kx = (wid >> 2) ? (1 - 2 * ks) * 1024 : 0;
;         bf16x8 At[8], Bf[4];
; #pragma unroll
;         for (int m = 0; m < 8; ++m) At[m] = *(const bf16x8*)(SAp + (2 * m + ks) * 1024 + kx);
; #pragma unroll
;         for (int n = 0; n < 4; ++n) Bf[n] = *(const bf16x8*)(SBp + (2 * n + ks) * 1024 + kx);
; #pragma unroll
;         for (int m = 0; m < 8; ++m)
; #pragma unroll
;           for (int n = 0; n < 4; ++n) acc[m][n] = mfma16(At[m], Bf[n], acc[m][n]);
;         __builtin_amdgcn_sched_barrier(0);
;         if (ks == 0 && wid >= 4) {
;           if (st_own) stage(cur ^ 1, n0, m0, kt0 + t + 1);
;           else if (st_next) stage(cur ^ 1, n1, m1, kt1);
;         }
;       }
;       asm volatile("s_waitcnt vmcnt(0)" ::: "memory");
;       __syncthreads();
.LBB0_1677:
.Lmy_xs_1678:
	s_waitcnt lgkmcnt(2)
	v_mfma_f32_16x16x32_bf16 v[124:127], v[220:223], v[134:137], v[124:127]
	v_mfma_f32_16x16x32_bf16 v[120:123], v[220:223], v[142:145], v[120:123]
	v_mfma_f32_16x16x32_bf16 v[116:119], v[220:223], v[146:149], v[116:119]
	v_mfma_f32_16x16x32_bf16 v[112:115], v[220:223], v[150:153], v[112:115]
	ds_read_b128 v[236:239], v154 offset:9216
	s_waitcnt lgkmcnt(3)
	v_mfma_f32_16x16x32_bf16 v[108:111], v[224:227], v[134:137], v[108:111]
	v_mfma_f32_16x16x32_bf16 v[104:107], v[224:227], v[142:145], v[104:107]
	v_mfma_f32_16x16x32_bf16 v[100:103], v[224:227], v[146:149], v[100:103]
	v_mfma_f32_16x16x32_bf16 v[96:99], v[224:227], v[150:153], v[96:99]
	ds_read_b128 v[240:243], v154 offset:11264
	s_waitcnt lgkmcnt(3)
	v_mfma_f32_16x16x32_bf16 v[92:95], v[228:231], v[134:137], v[92:95]
	v_mfma_f32_16x16x32_bf16 v[88:91], v[228:231], v[142:145], v[88:91]
	v_mfma_f32_16x16x32_bf16 v[84:87], v[228:231], v[146:149], v[84:87]
	v_mfma_f32_16x16x32_bf16 v[80:83], v[228:231], v[150:153], v[80:83]
	ds_read_b128 v[244:247], v154 offset:13312
	s_waitcnt lgkmcnt(3)
	v_mfma_f32_16x16x32_bf16 v[76:79], v[232:235], v[134:137], v[76:79]
	v_mfma_f32_16x16x32_bf16 v[72:75], v[232:235], v[142:145], v[72:75]
	v_mfma_f32_16x16x32_bf16 v[68:71], v[232:235], v[146:149], v[68:71]
	v_mfma_f32_16x16x32_bf16 v[64:67], v[232:235], v[150:153], v[64:67]
	ds_read_b128 v[248:251], v154 offset:15360
	s_waitcnt lgkmcnt(3)
	v_mfma_f32_16x16x32_bf16 v[60:63], v[236:239], v[134:137], v[60:63]
	v_mfma_f32_16x16x32_bf16 v[56:59], v[236:239], v[142:145], v[56:59]
	v_mfma_f32_16x16x32_bf16 v[52:55], v[236:239], v[146:149], v[52:55]
	v_mfma_f32_16x16x32_bf16 v[48:51], v[236:239], v[150:153], v[48:51]
	s_waitcnt lgkmcnt(2)
	v_mfma_f32_16x16x32_bf16 v[44:47], v[240:243], v[134:137], v[44:47]
	v_mfma_f32_16x16x32_bf16 v[40:43], v[240:243], v[142:145], v[40:43]
	v_mfma_f32_16x16x32_bf16 v[36:39], v[240:243], v[146:149], v[36:39]
	v_mfma_f32_16x16x32_bf16 v[32:35], v[240:243], v[150:153], v[32:35]
	s_addk_i32 s78, 0x80
	s_cmp_eq_u32 s77, s79
	s_cbranch_scc1 .Lmy_xexit_1678
	s_add_i32 s2, s61, s79
	s_and_b32 s80, s2, 1
	s_add_i32 s79, s79, 1
	s_cmp_lt_i32 s79, s60
	s_cselect_b64 s[2:3], -1, 0
	s_cmp_ge_i32 s79, s60
	s_cselect_b64 s[40:41], -1, 0
	v_cndmask_b32_e64 v128, 0, 1, s[2:3]
	s_and_b64 s[40:41], s[34:35], s[40:41]
	s_and_b64 vcc, exec, s[0:1]
	v_cmp_ne_u32_e64 s[2:3], 1, v128
	s_lshl_b32 s42, s80, 16
	s_add_i32 s16, s42, s57
	v_add_u32_e32 v129, s16, v194
	v_add_u32_e32 v253, s62, v129
	s_or_b32 s16, s42, s58
	v_add_u32_e32 v128, s16, v194
	v_add_u32_e32 v252, s62, v128
	s_waitcnt lgkmcnt(0)
	s_waitcnt vmcnt(0)
	s_barrier
	ds_read_b128 v[220:223], v253
	ds_read_b128 v[224:227], v253 offset:2048
	v_mfma_f32_16x16x32_bf16 v[28:31], v[244:247], v[134:137], v[28:31]
	v_mfma_f32_16x16x32_bf16 v[12:15], v[248:251], v[134:137], v[12:15]
	ds_read_b128 v[134:137], v252 offset:32768
	v_mfma_f32_16x16x32_bf16 v[24:27], v[244:247], v[142:145], v[24:27]
	v_mfma_f32_16x16x32_bf16 v[8:11], v[248:251], v[142:145], v[8:11]
	ds_read_b128 v[142:145], v252 offset:34816
	v_mfma_f32_16x16x32_bf16 v[20:23], v[244:247], v[146:149], v[20:23]
	v_mfma_f32_16x16x32_bf16 v[4:7], v[248:251], v[146:149], v[4:7]
	ds_read_b128 v[146:149], v252 offset:36864
	v_mfma_f32_16x16x32_bf16 v[16:19], v[244:247], v[150:153], v[16:19]
	v_mfma_f32_16x16x32_bf16 v[0:3], v[248:251], v[150:153], v[0:3]
	ds_read_b128 v[150:153], v252 offset:38912
	ds_read_b128 v[228:231], v253 offset:4096
	ds_read_b128 v[232:235], v253 offset:6144
	v_mov_b32_e32 v154, v253
	s_branch .Lmy_xf_1678

; DEVI f32x4 mfma16(bf16x8 a, bf16x8 b, f32x4 c) { return __builtin_amdgcn_mfma_f32_16x16x32_bf16(a, b, c, 0, 0, 0); }
; template <int MODE, class Epi>
; DEVI void gemm256_phase(int sw, const bf16_t* __restrict__ W, int ldw, const bf16_t* __restrict__ X, int ldx, int K, int nN, char* shm, const Epi& epi) {
;     ...
;   auto stage = [&](int buf, int n0, int m0, int kt) {
;     const char* wk = (const char*)(W + (size_t)n0 * ldw) + kt * 128;
;     const char* xk = (const char*)(X + (size_t)m0 * ldx) + kt * 128;
; #pragma unroll
;     for (int i = 0; i < 4; ++i) {
;       unsigned ow = offW[i], ox = offX[i];
;       asm volatile("" : "+v"(ow), "+v"(ox));
;       __builtin_amdgcn_global_load_lds((const unsigned*)(wk + ow), (unsigned*)(shm + buf * STAGE_B + wid * 1024 + i * 8192), 16, 0, 0);
;       __builtin_amdgcn_global_load_lds((const unsigned*)(xk + ox), (unsigned*)(shm + buf * STAGE_B + TILE_B + wid * 1024 + i * 8192), 16, 0, 0);
;     }
;     ...
; #pragma unroll
;       for (int ks = 0; ks < 2; ++ks) {
;         const int kx = (wid >> 2) ? (1 - 2 * ks) * 1024 : 0;
;         bf16x8 At[8], Bf[4];
; #pragma unroll
;         for (int m = 0; m < 8; ++m) At[m] = *(const bf16x8*)(SAp + (2 * m + ks) * 1024 + kx);
; #pragma unroll
;         for (int n = 0; n < 4; ++n) Bf[n] = *(const bf16x8*)(SBp + (2 * n + ks) * 1024 + kx);
; #pragma unroll
;         for (int m = 0; m < 8; ++m)
; #pragma unroll
;           for (int n = 0; n < 4; ++n) acc[m][n] = mfma16(At[m], Bf[n], acc[m][n]);
;         __builtin_amdgcn_sched_barrier(0);
;         if (ks == 0 && wid >= 4) {
;           if (st_own) stage(cur ^ 1, n0, m0, kt0 + t + 1);
;           else if (st_next) stage(cur ^ 1, n1, m1, kt1);
;         }
.Lmy_xf_1678:
	s_add_u32 s98, s73, s78
	s_addc_u32 s99, s74, 0
	s_add_u32 s98, s98, 0x80
	s_addc_u32 s99, s99, 0
	s_add_u32 s100, s75, s78
	s_addc_u32 s101, s76, 0
	s_add_u32 s100, s100, 0x80
	s_addc_u32 s101, s101, 0
	s_xor_b32 m0, s42, 0x10000
	s_add_i32 m0, m0, s56
	s_waitcnt lgkmcnt(2)
	v_mfma_f32_16x16x32_bf16 v[124:127], v[220:223], v[134:137], v[124:127]
	v_mfma_f32_16x16x32_bf16 v[120:123], v[220:223], v[142:145], v[120:123]
	v_mfma_f32_16x16x32_bf16 v[116:119], v[220:223], v[146:149], v[116:119]
	v_mfma_f32_16x16x32_bf16 v[112:115], v[220:223], v[150:153], v[112:115]
	global_load_lds_dwordx4 v190, s[98:99]
	ds_read_b128 v[236:239], v154 offset:8192
	s_add_i32 m0, m0, 0x8000
	s_waitcnt lgkmcnt(3)
	v_mfma_f32_16x16x32_bf16 v[108:111], v[224:227], v[134:137], v[108:111]
	v_mfma_f32_16x16x32_bf16 v[104:107], v[224:227], v[142:145], v[104:107]
	v_mfma_f32_16x16x32_bf16 v[100:103], v[224:227], v[146:149], v[100:103]
	v_mfma_f32_16x16x32_bf16 v[96:99], v[224:227], v[150:153], v[96:99]
	global_load_lds_dwordx4 v190, s[100:101]
	ds_read_b128 v[240:243], v154 offset:10240
	s_add_i32 m0, m0, 0xffffa000
	s_waitcnt lgkmcnt(3)
	v_mfma_f32_16x16x32_bf16 v[92:95], v[228:231], v[134:137], v[92:95]
	v_mfma_f32_16x16x32_bf16 v[88:91], v[228:231], v[142:145], v[88:91]
	v_mfma_f32_16x16x32_bf16 v[84:87], v[228:231], v[146:149], v[84:87]
	v_mfma_f32_16x16x32_bf16 v[80:83], v[228:231], v[150:153], v[80:83]
	global_load_lds_dwordx4 v191, s[98:99]
	ds_read_b128 v[244:247], v154 offset:12288
	s_add_i32 m0, m0, 0x8000
	s_waitcnt lgkmcnt(3)
	v_mfma_f32_16x16x32_bf16 v[76:79], v[232:235], v[134:137], v[76:79]
	v_mfma_f32_16x16x32_bf16 v[72:75], v[232:235], v[142:145], v[72:75]
	v_mfma_f32_16x16x32_bf16 v[68:71], v[232:235], v[146:149], v[68:71]
	v_mfma_f32_16x16x32_bf16 v[64:67], v[232:235], v[150:153], v[64:67]
	global_load_lds_dwordx4 v191, s[100:101]
	ds_read_b128 v[248:251], v154 offset:14336
	s_add_i32 m0, m0, 0xffffa000
	s_waitcnt lgkmcnt(3)
	v_mfma_f32_16x16x32_bf16 v[60:63], v[236:239], v[134:137], v[60:63]
	v_mfma_f32_16x16x32_bf16 v[56:59], v[236:239], v[142:145], v[56:59]
	v_mfma_f32_16x16x32_bf16 v[52:55], v[236:239], v[146:149], v[52:55]
	v_mfma_f32_16x16x32_bf16 v[48:51], v[236:239], v[150:153], v[48:51]
	global_load_lds_dwordx4 v192, s[98:99]
	s_add_i32 m0, m0, 0x8000
	s_waitcnt lgkmcnt(2)
	v_mfma_f32_16x16x32_bf16 v[44:47], v[240:243], v[134:137], v[44:47]
	v_mfma_f32_16x16x32_bf16 v[40:43], v[240:243], v[142:145], v[40:43]
	v_mfma_f32_16x16x32_bf16 v[36:39], v[240:243], v[146:149], v[36:39]
	v_mfma_f32_16x16x32_bf16 v[32:35], v[240:243], v[150:153], v[32:35]
	global_load_lds_dwordx4 v192, s[100:101]
	s_add_i32 m0, m0, 0xffffa000
	s_waitcnt lgkmcnt(0)
	v_add_u32_e32 v154, s63, v129
	v_add_u32_e32 v128, s63, v128
	ds_read_b128 v[220:223], v154 offset:1024
	ds_read_b128 v[224:227], v154 offset:3072
	v_mfma_f32_16x16x32_bf16 v[28:31], v[244:247], v[134:137], v[28:31]
	v_mfma_f32_16x16x32_bf16 v[12:15], v[248:251], v[134:137], v[12:15]
	ds_read_b128 v[134:137], v128 offset:33792
	v_mfma_f32_16x16x32_bf16 v[24:27], v[244:247], v[142:145], v[24:27]
	v_mfma_f32_16x16x32_bf16 v[8:11], v[248:251], v[142:145], v[8:11]
	ds_read_b128 v[142:145], v128 offset:35840
	global_load_lds_dwordx4 v193, s[98:99]
	s_add_i32 m0, m0, 0x8000
	v_mfma_f32_16x16x32_bf16 v[20:23], v[244:247], v[146:149], v[20:23]
	v_mfma_f32_16x16x32_bf16 v[4:7], v[248:251], v[146:149], v[4:7]
	ds_read_b128 v[146:149], v128 offset:37888
	v_mfma_f32_16x16x32_bf16 v[16:19], v[244:247], v[150:153], v[16:19]
	v_mfma_f32_16x16x32_bf16 v[0:3], v[248:251], v[150:153], v[0:3]
	ds_read_b128 v[150:153], v128 offset:39936
	global_load_lds_dwordx4 v193, s[100:101]
	ds_read_b128 v[228:231], v154 offset:5120
	ds_read_b128 v[232:235], v154 offset:7168
	s_andn2_b64 vcc, exec, s[8:9]
	s_branch .Lmy_xs_1678
	s_and_b64 vcc, exec, s[2:3]
	s_xor_b32 s48, s42, 0x10000
	s_cbranch_vccnz .LBB0_1690
	s_ashr_i32 s16, s78, 31
	s_add_u32 s44, s73, s78
	s_addc_u32 s45, s74, s16
	s_add_u32 s2, s44, 0x80
	s_addc_u32 s3, s45, 0
	s_add_u32 s46, s75, s78
	s_addc_u32 s47, s76, s16
	s_add_u32 s42, s46, 0x80
	v_mov_b32_e32 v130, v190
	v_mov_b32_e32 v188, v190
	s_addc_u32 s43, s47, 0
	s_add_i32 s16, s56, s48
	v_lshl_add_u64 v[132:133], s[44:45], 0, v[188:189]
	v_mov_b32_e32 v131, v189
	v_lshl_add_u64 v[132:133], v[132:133], 0, s[12:13]
	s_mov_b32 m0, s16
	v_lshl_add_u64 v[130:131], s[46:47], 0, v[130:131]
	global_load_lds_dwordx4 v[132:133], off
	v_lshl_add_u64 v[130:131], v[130:131], 0, s[12:13]
	s_add_i32 m0, s16, 0x8000
	v_mov_b32_e32 v188, v191
	global_load_lds_dwordx4 v[130:131], off
	v_mov_b32_e32 v130, v191
	v_mov_b32_e32 v131, v189
	v_lshl_add_u64 v[132:133], s[44:45], 0, v[188:189]
	v_lshl_add_u64 v[132:133], v[132:133], 0, s[12:13]
	s_add_i32 m0, s16, 0x2000
	v_lshl_add_u64 v[130:131], s[46:47], 0, v[130:131]
	global_load_lds_dwordx4 v[132:133], off
	v_lshl_add_u64 v[130:131], v[130:131], 0, s[12:13]
	s_add_i32 m0, s16, 0xa000
	v_mov_b32_e32 v188, v192
	global_load_lds_dwordx4 v[130:131], off
	v_mov_b32_e32 v130, v192
	v_mov_b32_e32 v131, v189
	v_lshl_add_u64 v[132:133], s[44:45], 0, v[188:189]
	v_lshl_add_u64 v[132:133], v[132:133], 0, s[12:13]
	s_add_i32 m0, s16, 0x4000
	v_lshl_add_u64 v[130:131], s[46:47], 0, v[130:131]
	global_load_lds_dwordx4 v[132:133], off
	v_lshl_add_u64 v[130:131], v[130:131], 0, s[12:13]
	s_add_i32 m0, s16, 0xc000
	s_nop 0
	global_load_lds_dwordx4 v[130:131], off
	v_mov_b32_e32 v130, v193
	v_mov_b32_e32 v131, v193
	s_mov_b64 s[44:45], -1
	s_cbranch_execz .LBB0_1691
	s_branch .LBB0_1694

; DEVI f32x4 mfma16(bf16x8 a, bf16x8 b, f32x4 c) { return __builtin_amdgcn_mfma_f32_16x16x32_bf16(a, b, c, 0, 0, 0); }
; template <int MODE, class Epi>
; DEVI void gemm256_phase(int sw, const bf16_t* __restrict__ W, int ldw, const bf16_t* __restrict__ X, int ldx, int K, int nN, char* shm, const Epi& epi) {
;     ...
; #pragma unroll
;       for (int ks = 0; ks < 2; ++ks) {
;         const int kx = (wid >> 2) ? (1 - 2 * ks) * 1024 : 0;
;         bf16x8 At[8], Bf[4];
; #pragma unroll
;         for (int m = 0; m < 8; ++m) At[m] = *(const bf16x8*)(SAp + (2 * m + ks) * 1024 + kx);
; #pragma unroll
;         for (int n = 0; n < 4; ++n) Bf[n] = *(const bf16x8*)(SBp + (2 * n + ks) * 1024 + kx);
; #pragma unroll
;         for (int m = 0; m < 8; ++m)
; #pragma unroll
;           for (int n = 0; n < 4; ++n) acc[m][n] = mfma16(At[m], Bf[n], acc[m][n]);
;         __builtin_amdgcn_sched_barrier(0);
;         if (ks == 0 && wid >= 4) {
;           if (st_own) stage(cur ^ 1, n0, m0, kt0 + t + 1);
;           else if (st_next) stage(cur ^ 1, n1, m1, kt1);
;         }
;       }
;       asm volatile("s_waitcnt vmcnt(0)" ::: "memory");
;       __syncthreads();
.LBB0_1759:
.Lmy_xs_1760:
	s_waitcnt lgkmcnt(2)
	v_mfma_f32_16x16x32_bf16 v[124:127], v[220:223], v[134:137], v[124:127]
	v_mfma_f32_16x16x32_bf16 v[120:123], v[220:223], v[142:145], v[120:123]
	v_mfma_f32_16x16x32_bf16 v[116:119], v[220:223], v[146:149], v[116:119]
	v_mfma_f32_16x16x32_bf16 v[112:115], v[220:223], v[150:153], v[112:115]
	ds_read_b128 v[236:239], v154 offset:9216
	s_waitcnt lgkmcnt(3)
	v_mfma_f32_16x16x32_bf16 v[108:111], v[224:227], v[134:137], v[108:111]
	v_mfma_f32_16x16x32_bf16 v[104:107], v[224:227], v[142:145], v[104:107]
	v_mfma_f32_16x16x32_bf16 v[100:103], v[224:227], v[146:149], v[100:103]
	v_mfma_f32_16x16x32_bf16 v[96:99], v[224:227], v[150:153], v[96:99]
	ds_read_b128 v[240:243], v154 offset:11264
	s_waitcnt lgkmcnt(3)
	v_mfma_f32_16x16x32_bf16 v[92:95], v[228:231], v[134:137], v[92:95]
	v_mfma_f32_16x16x32_bf16 v[88:91], v[228:231], v[142:145], v[88:91]
	v_mfma_f32_16x16x32_bf16 v[84:87], v[228:231], v[146:149], v[84:87]
	v_mfma_f32_16x16x32_bf16 v[80:83], v[228:231], v[150:153], v[80:83]
	ds_read_b128 v[244:247], v154 offset:13312
	s_waitcnt lgkmcnt(3)
	v_mfma_f32_16x16x32_bf16 v[76:79], v[232:235], v[134:137], v[76:79]
	v_mfma_f32_16x16x32_bf16 v[72:75], v[232:235], v[142:145], v[72:75]
	v_mfma_f32_16x16x32_bf16 v[68:71], v[232:235], v[146:149], v[68:71]
	v_mfma_f32_16x16x32_bf16 v[64:67], v[232:235], v[150:153], v[64:67]
	ds_read_b128 v[248:251], v154 offset:15360
	s_waitcnt lgkmcnt(3)
	v_mfma_f32_16x16x32_bf16 v[60:63], v[236:239], v[134:137], v[60:63]
	v_mfma_f32_16x16x32_bf16 v[56:59], v[236:239], v[142:145], v[56:59]
	v_mfma_f32_16x16x32_bf16 v[52:55], v[236:239], v[146:149], v[52:55]
	v_mfma_f32_16x16x32_bf16 v[48:51], v[236:239], v[150:153], v[48:51]
	s_waitcnt lgkmcnt(2)
	v_mfma_f32_16x16x32_bf16 v[44:47], v[240:243], v[134:137], v[44:47]
	v_mfma_f32_16x16x32_bf16 v[40:43], v[240:243], v[142:145], v[40:43]
	v_mfma_f32_16x16x32_bf16 v[36:39], v[240:243], v[146:149], v[36:39]
	v_mfma_f32_16x16x32_bf16 v[32:35], v[240:243], v[150:153], v[32:35]
	s_addk_i32 s49, 0x80
	s_cmp_eq_u32 s46, s50
	s_cbranch_scc1 .Lmy_xexit_1760
	s_add_i32 s10, s31, s50
	s_and_b32 s52, s10, 1
	s_mov_b64 s[10:11], -1
	s_and_b64 vcc, exec, s[4:5]
	s_lshl_b32 s51, s52, 16
	s_add_i32 s10, s51, s34
	v_add_u32_e32 v129, s10, v198
	v_add_u32_e32 v253, s37, v129
	s_add_i32 s10, s51, s35
	v_add_u32_e32 v128, s10, v198
	v_add_u32_e32 v252, s37, v128
	s_waitcnt lgkmcnt(0)
	s_waitcnt vmcnt(0)
	s_barrier
	ds_read_b128 v[220:223], v253
	ds_read_b128 v[224:227], v253 offset:2048
	v_mfma_f32_16x16x32_bf16 v[28:31], v[244:247], v[134:137], v[28:31]
	v_mfma_f32_16x16x32_bf16 v[12:15], v[248:251], v[134:137], v[12:15]
	ds_read_b128 v[134:137], v252 offset:32768
	v_mfma_f32_16x16x32_bf16 v[24:27], v[244:247], v[142:145], v[24:27]
	v_mfma_f32_16x16x32_bf16 v[8:11], v[248:251], v[142:145], v[8:11]
	ds_read_b128 v[142:145], v252 offset:34816
	v_mfma_f32_16x16x32_bf16 v[20:23], v[244:247], v[146:149], v[20:23]
	v_mfma_f32_16x16x32_bf16 v[4:7], v[248:251], v[146:149], v[4:7]
	ds_read_b128 v[146:149], v252 offset:36864
	v_mfma_f32_16x16x32_bf16 v[16:19], v[244:247], v[150:153], v[16:19]
	v_mfma_f32_16x16x32_bf16 v[0:3], v[248:251], v[150:153], v[0:3]
	ds_read_b128 v[150:153], v252 offset:38912
	ds_read_b128 v[228:231], v253 offset:4096
	ds_read_b128 v[232:235], v253 offset:6144
	v_mov_b32_e32 v154, v253
	s_branch .Lmy_xf_1760

; DEVI f32x4 mfma16(bf16x8 a, bf16x8 b, f32x4 c) { return __builtin_amdgcn_mfma_f32_16x16x32_bf16(a, b, c, 0, 0, 0); }
; template <int MODE, class Epi>
; DEVI void gemm256_phase(int sw, const bf16_t* __restrict__ W, int ldw, const bf16_t* __restrict__ X, int ldx, int K, int nN, char* shm, const Epi& epi) {
;     ...
;   auto stage = [&](int buf, int n0, int m0, int kt) {
;     const char* wk = (const char*)(W + (size_t)n0 * ldw) + kt * 128;
;     const char* xk = (const char*)(X + (size_t)m0 * ldx) + kt * 128;
; #pragma unroll
;     for (int i = 0; i < 4; ++i) {
;       unsigned ow = offW[i], ox = offX[i];
;       asm volatile("" : "+v"(ow), "+v"(ox));
;       __builtin_amdgcn_global_load_lds((const unsigned*)(wk + ow), (unsigned*)(shm + buf * STAGE_B + wid * 1024 + i * 8192), 16, 0, 0);
;       __builtin_amdgcn_global_load_lds((const unsigned*)(xk + ox), (unsigned*)(shm + buf * STAGE_B + TILE_B + wid * 1024 + i * 8192), 16, 0, 0);
;     }
;     ...
; #pragma unroll
;       for (int ks = 0; ks < 2; ++ks) {
;         const int kx = (wid >> 2) ? (1 - 2 * ks) * 1024 : 0;
;         bf16x8 At[8], Bf[4];
; #pragma unroll
;         for (int m = 0; m < 8; ++m) At[m] = *(const bf16x8*)(SAp + (2 * m + ks) * 1024 + kx);
; #pragma unroll
;         for (int n = 0; n < 4; ++n) Bf[n] = *(const bf16x8*)(SBp + (2 * n + ks) * 1024 + kx);
; #pragma unroll
;         for (int m = 0; m < 8; ++m)
; #pragma unroll
;           for (int n = 0; n < 4; ++n) acc[m][n] = mfma16(At[m], Bf[n], acc[m][n]);
;         __builtin_amdgcn_sched_barrier(0);
;         if (ks == 0 && wid >= 4) {
;           if (st_own) stage(cur ^ 1, n0, m0, kt0 + t + 1);
;           else if (st_next) stage(cur ^ 1, n1, m1, kt1);
;         }
.Lmy_xf_1760:
	s_add_u32 s98, s12, s49
	s_addc_u32 s99, s13, 0
	s_add_u32 s98, s98, 0x80
	s_addc_u32 s99, s99, 0
	s_add_u32 s100, s47, s49
	s_addc_u32 s101, s48, 0
	s_add_u32 s100, s100, 0x80
	s_addc_u32 s101, s101, 0
	s_xor_b32 m0, s51, 0x10000
	s_add_i32 m0, m0, s14
	s_waitcnt lgkmcnt(2)
	v_mfma_f32_16x16x32_bf16 v[124:127], v[220:223], v[134:137], v[124:127]
	v_mfma_f32_16x16x32_bf16 v[120:123], v[220:223], v[142:145], v[120:123]
	v_mfma_f32_16x16x32_bf16 v[116:119], v[220:223], v[146:149], v[116:119]
	v_mfma_f32_16x16x32_bf16 v[112:115], v[220:223], v[150:153], v[112:115]
	global_load_lds_dwordx4 v194, s[98:99]
	ds_read_b128 v[236:239], v154 offset:8192
	s_add_i32 m0, m0, 0x8000
	s_waitcnt lgkmcnt(3)
	v_mfma_f32_16x16x32_bf16 v[108:111], v[224:227], v[134:137], v[108:111]
	v_mfma_f32_16x16x32_bf16 v[104:107], v[224:227], v[142:145], v[104:107]
	v_mfma_f32_16x16x32_bf16 v[100:103], v[224:227], v[146:149], v[100:103]
	v_mfma_f32_16x16x32_bf16 v[96:99], v[224:227], v[150:153], v[96:99]
	global_load_lds_dwordx4 v194, s[100:101]
	ds_read_b128 v[240:243], v154 offset:10240
	s_add_i32 m0, m0, 0xffffa000
	s_waitcnt lgkmcnt(3)
	v_mfma_f32_16x16x32_bf16 v[92:95], v[228:231], v[134:137], v[92:95]
	v_mfma_f32_16x16x32_bf16 v[88:91], v[228:231], v[142:145], v[88:91]
	v_mfma_f32_16x16x32_bf16 v[84:87], v[228:231], v[146:149], v[84:87]
	v_mfma_f32_16x16x32_bf16 v[80:83], v[228:231], v[150:153], v[80:83]
	global_load_lds_dwordx4 v195, s[98:99]
	ds_read_b128 v[244:247], v154 offset:12288
	s_add_i32 m0, m0, 0x8000
	s_waitcnt lgkmcnt(3)
	v_mfma_f32_16x16x32_bf16 v[76:79], v[232:235], v[134:137], v[76:79]
	v_mfma_f32_16x16x32_bf16 v[72:75], v[232:235], v[142:145], v[72:75]
	v_mfma_f32_16x16x32_bf16 v[68:71], v[232:235], v[146:149], v[68:71]
	v_mfma_f32_16x16x32_bf16 v[64:67], v[232:235], v[150:153], v[64:67]
	global_load_lds_dwordx4 v195, s[100:101]
	ds_read_b128 v[248:251], v154 offset:14336
	s_add_i32 m0, m0, 0xffffa000
	s_waitcnt lgkmcnt(3)
	v_mfma_f32_16x16x32_bf16 v[60:63], v[236:239], v[134:137], v[60:63]
	v_mfma_f32_16x16x32_bf16 v[56:59], v[236:239], v[142:145], v[56:59]
	v_mfma_f32_16x16x32_bf16 v[52:55], v[236:239], v[146:149], v[52:55]
	v_mfma_f32_16x16x32_bf16 v[48:51], v[236:239], v[150:153], v[48:51]
	global_load_lds_dwordx4 v196, s[98:99]
	s_add_i32 m0, m0, 0x8000
	s_waitcnt lgkmcnt(2)
	v_mfma_f32_16x16x32_bf16 v[44:47], v[240:243], v[134:137], v[44:47]
	v_mfma_f32_16x16x32_bf16 v[40:43], v[240:243], v[142:145], v[40:43]
	v_mfma_f32_16x16x32_bf16 v[36:39], v[240:243], v[146:149], v[36:39]
	v_mfma_f32_16x16x32_bf16 v[32:35], v[240:243], v[150:153], v[32:35]
	global_load_lds_dwordx4 v196, s[100:101]
	s_add_i32 m0, m0, 0xffffa000
	s_waitcnt lgkmcnt(0)
	v_add_u32_e32 v154, s38, v129
	v_add_u32_e32 v128, s38, v128
	s_add_i32 s50, s50, 1
	ds_read_b128 v[220:223], v154 offset:1024
	ds_read_b128 v[224:227], v154 offset:3072
	v_mfma_f32_16x16x32_bf16 v[28:31], v[244:247], v[134:137], v[28:31]
	v_mfma_f32_16x16x32_bf16 v[12:15], v[248:251], v[134:137], v[12:15]
	ds_read_b128 v[134:137], v128 offset:33792
	v_mfma_f32_16x16x32_bf16 v[24:27], v[244:247], v[142:145], v[24:27]
	v_mfma_f32_16x16x32_bf16 v[8:11], v[248:251], v[142:145], v[8:11]
	ds_read_b128 v[142:145], v128 offset:35840
	global_load_lds_dwordx4 v197, s[98:99]
	s_add_i32 m0, m0, 0x8000
	v_mfma_f32_16x16x32_bf16 v[20:23], v[244:247], v[146:149], v[20:23]
	v_mfma_f32_16x16x32_bf16 v[4:7], v[248:251], v[146:149], v[4:7]
	ds_read_b128 v[146:149], v128 offset:37888
	v_mfma_f32_16x16x32_bf16 v[16:19], v[244:247], v[150:153], v[16:19]
	v_mfma_f32_16x16x32_bf16 v[0:3], v[248:251], v[150:153], v[0:3]
	ds_read_b128 v[150:153], v128 offset:39936
	global_load_lds_dwordx4 v197, s[100:101]
	ds_read_b128 v[228:231], v154 offset:5120
	ds_read_b128 v[232:235], v154 offset:7168
	s_and_b64 vcc, exec, s[0:1]
	s_branch .Lmy_xs_1760
	s_xor_b32 s10, s51, 0x10000
	s_add_i32 s16, s14, s10
	s_add_i32 s17, s16, 0xe000
	s_add_i32 s18, s16, 0x6000
	s_add_i32 s19, s16, 0xc000
	s_add_i32 s28, s16, 0x4000
	s_add_i32 s29, s16, 0xa000
	s_add_i32 s33, s16, 0x2000
	s_add_i32 s51, s16, 0x8000
	s_ashr_i32 s53, s49, 31
	s_add_u32 s10, s47, s49
	s_addc_u32 s11, s48, s53
	s_add_u32 s52, s12, s49
	s_addc_u32 s53, s13, s53
	v_mov_b32_e32 v192, v194
	v_mov_b32_e32 v130, v194
	v_mov_b32_e32 v131, v193
	v_lshl_add_u64 v[132:133], s[52:53], 0, v[192:193]
	v_lshl_add_u64 v[132:133], v[132:133], 0, s[6:7]
	s_mov_b32 m0, s16
	v_lshl_add_u64 v[130:131], s[10:11], 0, v[130:131]
	global_load_lds_dwordx4 v[132:133], off
	v_lshl_add_u64 v[130:131], v[130:131], 0, s[6:7]
	s_mov_b32 m0, s51
	v_mov_b32_e32 v192, v195
	global_load_lds_dwordx4 v[130:131], off
	v_mov_b32_e32 v130, v195
	v_mov_b32_e32 v131, v193
	v_lshl_add_u64 v[132:133], s[52:53], 0, v[192:193]
	v_lshl_add_u64 v[132:133], v[132:133], 0, s[6:7]
	s_mov_b32 m0, s33
	v_lshl_add_u64 v[130:131], s[10:11], 0, v[130:131]
	global_load_lds_dwordx4 v[132:133], off
	v_lshl_add_u64 v[130:131], v[130:131], 0, s[6:7]
	s_mov_b32 m0, s29
	v_mov_b32_e32 v192, v196
	global_load_lds_dwordx4 v[130:131], off
	v_mov_b32_e32 v130, v196
	v_mov_b32_e32 v131, v193
	v_lshl_add_u64 v[132:133], s[52:53], 0, v[192:193]
	v_lshl_add_u64 v[132:133], v[132:133], 0, s[6:7]
	s_mov_b32 m0, s28
	v_lshl_add_u64 v[130:131], s[10:11], 0, v[130:131]
	global_load_lds_dwordx4 v[132:133], off
	v_lshl_add_u64 v[130:131], v[130:131], 0, s[6:7]
	s_mov_b32 m0, s19
	v_mov_b32_e32 v192, v197
	global_load_lds_dwordx4 v[130:131], off
	v_mov_b32_e32 v130, v197
	v_mov_b32_e32 v131, v193
	v_lshl_add_u64 v[132:133], s[52:53], 0, v[192:193]
	v_lshl_add_u64 v[132:133], v[132:133], 0, s[6:7]
	s_mov_b32 m0, s18
	v_lshl_add_u64 v[130:131], s[10:11], 0, v[130:131]
	global_load_lds_dwordx4 v[132:133], off
	v_lshl_add_u64 v[130:131], v[130:131], 0, s[6:7]
	s_mov_b32 m0, s17
	s_nop 0
	global_load_lds_dwordx4 v[130:131], off
	s_branch .LBB0_1759

; DEVI f32x4 mfma16(bf16x8 a, bf16x8 b, f32x4 c) { return __builtin_amdgcn_mfma_f32_16x16x32_bf16(a, b, c, 0, 0, 0); }
; template <int MODE, class Epi>
; DEVI void gemm256_phase(int sw, const bf16_t* __restrict__ W, int ldw, const bf16_t* __restrict__ X, int ldx, int K, int nN, char* shm, const Epi& epi) {
;     ...
; #pragma unroll
;       for (int ks = 0; ks < 2; ++ks) {
;         const int kx = (wid >> 2) ? (1 - 2 * ks) * 1024 : 0;
;         bf16x8 At[8], Bf[4];
; #pragma unroll
;         for (int m = 0; m < 8; ++m) At[m] = *(const bf16x8*)(SAp + (2 * m + ks) * 1024 + kx);
; #pragma unroll
;         for (int n = 0; n < 4; ++n) Bf[n] = *(const bf16x8*)(SBp + (2 * n + ks) * 1024 + kx);
; #pragma unroll
;         for (int m = 0; m < 8; ++m)
; #pragma unroll
;           for (int n = 0; n < 4; ++n) acc[m][n] = mfma16(At[m], Bf[n], acc[m][n]);
;         __builtin_amdgcn_sched_barrier(0);
;         if (ks == 0 && wid >= 4) {
;           if (st_own) stage(cur ^ 1, n0, m0, kt0 + t + 1);
;           else if (st_next) stage(cur ^ 1, n1, m1, kt1);
;         }
;       }
;       asm volatile("s_waitcnt vmcnt(0)" ::: "memory");
;       __syncthreads();
.LBB0_1800:
.Lmy_xs_1801:
	s_waitcnt lgkmcnt(2)
	v_mfma_f32_16x16x32_bf16 v[124:127], v[220:223], v[134:137], v[124:127]
	v_mfma_f32_16x16x32_bf16 v[120:123], v[220:223], v[142:145], v[120:123]
	v_mfma_f32_16x16x32_bf16 v[116:119], v[220:223], v[146:149], v[116:119]
	v_mfma_f32_16x16x32_bf16 v[112:115], v[220:223], v[150:153], v[112:115]
	ds_read_b128 v[236:239], v154 offset:9216
	s_waitcnt lgkmcnt(3)
	v_mfma_f32_16x16x32_bf16 v[108:111], v[224:227], v[134:137], v[108:111]
	v_mfma_f32_16x16x32_bf16 v[104:107], v[224:227], v[142:145], v[104:107]
	v_mfma_f32_16x16x32_bf16 v[100:103], v[224:227], v[146:149], v[100:103]
	v_mfma_f32_16x16x32_bf16 v[96:99], v[224:227], v[150:153], v[96:99]
	ds_read_b128 v[240:243], v154 offset:11264
	s_waitcnt lgkmcnt(3)
	v_mfma_f32_16x16x32_bf16 v[92:95], v[228:231], v[134:137], v[92:95]
	v_mfma_f32_16x16x32_bf16 v[88:91], v[228:231], v[142:145], v[88:91]
	v_mfma_f32_16x16x32_bf16 v[84:87], v[228:231], v[146:149], v[84:87]
	v_mfma_f32_16x16x32_bf16 v[80:83], v[228:231], v[150:153], v[80:83]
	ds_read_b128 v[244:247], v154 offset:13312
	s_waitcnt lgkmcnt(3)
	v_mfma_f32_16x16x32_bf16 v[76:79], v[232:235], v[134:137], v[76:79]
	v_mfma_f32_16x16x32_bf16 v[72:75], v[232:235], v[142:145], v[72:75]
	v_mfma_f32_16x16x32_bf16 v[68:71], v[232:235], v[146:149], v[68:71]
	v_mfma_f32_16x16x32_bf16 v[64:67], v[232:235], v[150:153], v[64:67]
	ds_read_b128 v[248:251], v154 offset:15360
	s_waitcnt lgkmcnt(3)
	v_mfma_f32_16x16x32_bf16 v[60:63], v[236:239], v[134:137], v[60:63]
	v_mfma_f32_16x16x32_bf16 v[56:59], v[236:239], v[142:145], v[56:59]
	v_mfma_f32_16x16x32_bf16 v[52:55], v[236:239], v[146:149], v[52:55]
	v_mfma_f32_16x16x32_bf16 v[48:51], v[236:239], v[150:153], v[48:51]
	s_waitcnt lgkmcnt(2)
	v_mfma_f32_16x16x32_bf16 v[44:47], v[240:243], v[134:137], v[44:47]
	v_mfma_f32_16x16x32_bf16 v[40:43], v[240:243], v[142:145], v[40:43]
	v_mfma_f32_16x16x32_bf16 v[36:39], v[240:243], v[146:149], v[36:39]
	v_mfma_f32_16x16x32_bf16 v[32:35], v[240:243], v[150:153], v[32:35]
	s_addk_i32 s69, 0x80
	s_cmp_eq_u32 s68, s70
	s_cbranch_scc1 .Lmy_xexit_1801
	s_add_i32 s2, s52, s70
	s_and_b32 s71, s2, 1
	s_add_i32 s70, s70, 1
	s_cmp_lt_i32 s70, s58
	s_cselect_b64 s[2:3], -1, 0
	s_cmp_ge_i32 s70, s58
	s_cselect_b64 s[36:37], -1, 0
	v_cndmask_b32_e64 v128, 0, 1, s[2:3]
	s_and_b64 s[36:37], s[28:29], s[36:37]
	s_and_b64 vcc, exec, s[0:1]
	v_cmp_ne_u32_e64 s[2:3], 1, v128
	s_lshl_b32 s38, s71, 16
	s_add_i32 s16, s38, s49
	v_add_u32_e32 v129, s16, v194
	v_add_u32_e32 v253, s53, v129
	s_or_b32 s16, s38, s50
	v_add_u32_e32 v128, s16, v194
	v_add_u32_e32 v252, s53, v128
	s_waitcnt lgkmcnt(0)
	s_waitcnt vmcnt(0)
	s_barrier
	ds_read_b128 v[220:223], v253
	ds_read_b128 v[224:227], v253 offset:2048
	v_mfma_f32_16x16x32_bf16 v[28:31], v[244:247], v[134:137], v[28:31]
	v_mfma_f32_16x16x32_bf16 v[12:15], v[248:251], v[134:137], v[12:15]
	ds_read_b128 v[134:137], v252 offset:32768
	v_mfma_f32_16x16x32_bf16 v[24:27], v[244:247], v[142:145], v[24:27]
	v_mfma_f32_16x16x32_bf16 v[8:11], v[248:251], v[142:145], v[8:11]
	ds_read_b128 v[142:145], v252 offset:34816
	v_mfma_f32_16x16x32_bf16 v[20:23], v[244:247], v[146:149], v[20:23]
	v_mfma_f32_16x16x32_bf16 v[4:7], v[248:251], v[146:149], v[4:7]
	ds_read_b128 v[146:149], v252 offset:36864
	v_mfma_f32_16x16x32_bf16 v[16:19], v[244:247], v[150:153], v[16:19]
	v_mfma_f32_16x16x32_bf16 v[0:3], v[248:251], v[150:153], v[0:3]
	ds_read_b128 v[150:153], v252 offset:38912
	ds_read_b128 v[228:231], v253 offset:4096
	ds_read_b128 v[232:235], v253 offset:6144
	v_mov_b32_e32 v154, v253
	s_branch .Lmy_xf_1801

; DEVI f32x4 mfma16(bf16x8 a, bf16x8 b, f32x4 c) { return __builtin_amdgcn_mfma_f32_16x16x32_bf16(a, b, c, 0, 0, 0); }
; template <int MODE, class Epi>
; DEVI void gemm256_phase(int sw, const bf16_t* __restrict__ W, int ldw, const bf16_t* __restrict__ X, int ldx, int K, int nN, char* shm, const Epi& epi) {
;     ...
;   auto stage = [&](int buf, int n0, int m0, int kt) {
;     const char* wk = (const char*)(W + (size_t)n0 * ldw) + kt * 128;
;     const char* xk = (const char*)(X + (size_t)m0 * ldx) + kt * 128;
; #pragma unroll
;     for (int i = 0; i < 4; ++i) {
;       unsigned ow = offW[i], ox = offX[i];
;       asm volatile("" : "+v"(ow), "+v"(ox));
;       __builtin_amdgcn_global_load_lds((const unsigned*)(wk + ow), (unsigned*)(shm + buf * STAGE_B + wid * 1024 + i * 8192), 16, 0, 0);
;       __builtin_amdgcn_global_load_lds((const unsigned*)(xk + ox), (unsigned*)(shm + buf * STAGE_B + TILE_B + wid * 1024 + i * 8192), 16, 0, 0);
;     }
;     ...
; #pragma unroll
;       for (int ks = 0; ks < 2; ++ks) {
;         const int kx = (wid >> 2) ? (1 - 2 * ks) * 1024 : 0;
;         bf16x8 At[8], Bf[4];
; #pragma unroll
;         for (int m = 0; m < 8; ++m) At[m] = *(const bf16x8*)(SAp + (2 * m + ks) * 1024 + kx);
; #pragma unroll
;         for (int n = 0; n < 4; ++n) Bf[n] = *(const bf16x8*)(SBp + (2 * n + ks) * 1024 + kx);
; #pragma unroll
;         for (int m = 0; m < 8; ++m)
; #pragma unroll
;           for (int n = 0; n < 4; ++n) acc[m][n] = mfma16(At[m], Bf[n], acc[m][n]);
;         __builtin_amdgcn_sched_barrier(0);
;         if (ks == 0 && wid >= 4) {
;           if (st_own) stage(cur ^ 1, n0, m0, kt0 + t + 1);
;           else if (st_next) stage(cur ^ 1, n1, m1, kt1);
;         }
.Lmy_xf_1801:
	s_add_u32 s98, s64, s69
	s_addc_u32 s99, s65, 0
	s_add_u32 s98, s98, 0x80
	s_addc_u32 s99, s99, 0
	s_add_u32 s100, s66, s69
	s_addc_u32 s101, s67, 0
	s_add_u32 s100, s100, 0x80
	s_addc_u32 s101, s101, 0
	s_xor_b32 m0, s38, 0x10000
	s_add_i32 m0, m0, s48
	s_waitcnt lgkmcnt(2)
	v_mfma_f32_16x16x32_bf16 v[124:127], v[220:223], v[134:137], v[124:127]
	v_mfma_f32_16x16x32_bf16 v[120:123], v[220:223], v[142:145], v[120:123]
	v_mfma_f32_16x16x32_bf16 v[116:119], v[220:223], v[146:149], v[116:119]
	v_mfma_f32_16x16x32_bf16 v[112:115], v[220:223], v[150:153], v[112:115]
	global_load_lds_dwordx4 v190, s[98:99]
	ds_read_b128 v[236:239], v154 offset:8192
	s_add_i32 m0, m0, 0x8000
	s_waitcnt lgkmcnt(3)
	v_mfma_f32_16x16x32_bf16 v[108:111], v[224:227], v[134:137], v[108:111]
	v_mfma_f32_16x16x32_bf16 v[104:107], v[224:227], v[142:145], v[104:107]
	v_mfma_f32_16x16x32_bf16 v[100:103], v[224:227], v[146:149], v[100:103]
	v_mfma_f32_16x16x32_bf16 v[96:99], v[224:227], v[150:153], v[96:99]
	global_load_lds_dwordx4 v190, s[100:101]
	ds_read_b128 v[240:243], v154 offset:10240
	s_add_i32 m0, m0, 0xffffa000
	s_waitcnt lgkmcnt(3)
	v_mfma_f32_16x16x32_bf16 v[92:95], v[228:231], v[134:137], v[92:95]
	v_mfma_f32_16x16x32_bf16 v[88:91], v[228:231], v[142:145], v[88:91]
	v_mfma_f32_16x16x32_bf16 v[84:87], v[228:231], v[146:149], v[84:87]
	v_mfma_f32_16x16x32_bf16 v[80:83], v[228:231], v[150:153], v[80:83]
	global_load_lds_dwordx4 v191, s[98:99]
	ds_read_b128 v[244:247], v154 offset:12288
	s_add_i32 m0, m0, 0x8000
	s_waitcnt lgkmcnt(3)
	v_mfma_f32_16x16x32_bf16 v[76:79], v[232:235], v[134:137], v[76:79]
	v_mfma_f32_16x16x32_bf16 v[72:75], v[232:235], v[142:145], v[72:75]
	v_mfma_f32_16x16x32_bf16 v[68:71], v[232:235], v[146:149], v[68:71]
	v_mfma_f32_16x16x32_bf16 v[64:67], v[232:235], v[150:153], v[64:67]
	global_load_lds_dwordx4 v191, s[100:101]
	ds_read_b128 v[248:251], v154 offset:14336
	s_add_i32 m0, m0, 0xffffa000
	s_waitcnt lgkmcnt(3)
	v_mfma_f32_16x16x32_bf16 v[60:63], v[236:239], v[134:137], v[60:63]
	v_mfma_f32_16x16x32_bf16 v[56:59], v[236:239], v[142:145], v[56:59]
	v_mfma_f32_16x16x32_bf16 v[52:55], v[236:239], v[146:149], v[52:55]
	v_mfma_f32_16x16x32_bf16 v[48:51], v[236:239], v[150:153], v[48:51]
	global_load_lds_dwordx4 v192, s[98:99]
	s_add_i32 m0, m0, 0x8000
	s_waitcnt lgkmcnt(2)
	v_mfma_f32_16x16x32_bf16 v[44:47], v[240:243], v[134:137], v[44:47]
	v_mfma_f32_16x16x32_bf16 v[40:43], v[240:243], v[142:145], v[40:43]
	v_mfma_f32_16x16x32_bf16 v[36:39], v[240:243], v[146:149], v[36:39]
	v_mfma_f32_16x16x32_bf16 v[32:35], v[240:243], v[150:153], v[32:35]
	global_load_lds_dwordx4 v192, s[100:101]
	s_add_i32 m0, m0, 0xffffa000
	s_waitcnt lgkmcnt(0)
	v_add_u32_e32 v154, s54, v129
	v_add_u32_e32 v128, s54, v128
	ds_read_b128 v[220:223], v154 offset:1024
	ds_read_b128 v[224:227], v154 offset:3072
	v_mfma_f32_16x16x32_bf16 v[28:31], v[244:247], v[134:137], v[28:31]
	v_mfma_f32_16x16x32_bf16 v[12:15], v[248:251], v[134:137], v[12:15]
	ds_read_b128 v[134:137], v128 offset:33792
	v_mfma_f32_16x16x32_bf16 v[24:27], v[244:247], v[142:145], v[24:27]
	v_mfma_f32_16x16x32_bf16 v[8:11], v[248:251], v[142:145], v[8:11]
	ds_read_b128 v[142:145], v128 offset:35840
	global_load_lds_dwordx4 v193, s[98:99]
	s_add_i32 m0, m0, 0x8000
	v_mfma_f32_16x16x32_bf16 v[20:23], v[244:247], v[146:149], v[20:23]
	v_mfma_f32_16x16x32_bf16 v[4:7], v[248:251], v[146:149], v[4:7]
	ds_read_b128 v[146:149], v128 offset:37888
	v_mfma_f32_16x16x32_bf16 v[16:19], v[244:247], v[150:153], v[16:19]
	v_mfma_f32_16x16x32_bf16 v[0:3], v[248:251], v[150:153], v[0:3]
	ds_read_b128 v[150:153], v128 offset:39936
	global_load_lds_dwordx4 v193, s[100:101]
	ds_read_b128 v[228:231], v154 offset:5120
	ds_read_b128 v[232:235], v154 offset:7168
	s_andn2_b64 vcc, exec, s[8:9]
	s_branch .Lmy_xs_1801
	s_and_b64 vcc, exec, s[2:3]
	s_xor_b32 s44, s38, 0x10000
	s_cbranch_vccnz .LBB0_1813
	s_ashr_i32 s16, s69, 31
	s_add_u32 s40, s64, s69
	s_addc_u32 s41, s65, s16
	s_add_u32 s2, s40, 0x80
	s_addc_u32 s3, s41, 0
	s_add_u32 s42, s66, s69
	s_addc_u32 s43, s67, s16
	s_add_u32 s38, s42, 0x80
	v_mov_b32_e32 v188, v190
	v_mov_b32_e32 v130, v190
	s_addc_u32 s39, s43, 0
	s_add_i32 s16, s48, s44
	v_lshl_add_u64 v[132:133], s[40:41], 0, v[188:189]
	v_mov_b32_e32 v131, v189
	v_lshl_add_u64 v[132:133], v[132:133], 0, s[12:13]
	s_mov_b32 m0, s16
	v_lshl_add_u64 v[130:131], s[42:43], 0, v[130:131]
	global_load_lds_dwordx4 v[132:133], off
	v_lshl_add_u64 v[130:131], v[130:131], 0, s[12:13]
	s_add_i32 m0, s16, 0x8000
	v_mov_b32_e32 v188, v191
	global_load_lds_dwordx4 v[130:131], off
	v_mov_b32_e32 v130, v191
	v_mov_b32_e32 v131, v189
	v_lshl_add_u64 v[132:133], s[40:41], 0, v[188:189]
	v_lshl_add_u64 v[132:133], v[132:133], 0, s[12:13]
	s_add_i32 m0, s16, 0x2000
	v_lshl_add_u64 v[130:131], s[42:43], 0, v[130:131]
	global_load_lds_dwordx4 v[132:133], off
	v_lshl_add_u64 v[130:131], v[130:131], 0, s[12:13]
	s_add_i32 m0, s16, 0xa000
	v_mov_b32_e32 v188, v192
	global_load_lds_dwordx4 v[130:131], off
	v_mov_b32_e32 v130, v192
	v_mov_b32_e32 v131, v189
	v_lshl_add_u64 v[132:133], s[40:41], 0, v[188:189]
	v_lshl_add_u64 v[132:133], v[132:133], 0, s[12:13]
	s_add_i32 m0, s16, 0x4000
	v_lshl_add_u64 v[130:131], s[42:43], 0, v[130:131]
	global_load_lds_dwordx4 v[132:133], off
	v_lshl_add_u64 v[130:131], v[130:131], 0, s[12:13]
	s_add_i32 m0, s16, 0xc000
	s_nop 0
	global_load_lds_dwordx4 v[130:131], off
	v_mov_b32_e32 v130, v193
	v_mov_b32_e32 v131, v193
	s_mov_b64 s[40:41], -1
	s_cbranch_execz .LBB0_1814
	s_branch .LBB0_1817
